# lagging wave half takes its per-unit pairing barrier in the peeled first K-iteration instead of at the unit-loop latch (both halves restart the next unit concurrently)
# speedup vs baseline: 1.0090x; 1.0004x over previous
.LBB0_174:
	v_lshrrev_b32_e32 v18, 1, v15
	s_add_u32 s46, s9, 0x19c00000
	v_and_b32_e32 v18, 24, v18
	s_addc_u32 s47, s10, 0
	v_and_b32_e32 v16, 15, v15
	s_lshl_b32 s17, s1, 6
	v_lshlrev_b32_e32 v19, 1, v18
	v_lshlrev_b32_e32 v15, 2, v15
	s_and_b32 s6, s0, 3
	v_or_b32_e32 v17, s17, v16
	v_lshl_or_b32 v16, v16, 6, v19
	s_lshl_b32 s0, s1, 13
	v_and_b32_e32 v15, 32, v15
	s_add_i32 m0, s73, 0x18000
	v_lshl_add_u64 v[8:9], v[8:9], 0, s[24:25]
	v_bitop3_b32 v19, v16, s0, v15 bitop3:0xde
	s_lshl_b32 s0, s6, 12
	s_waitcnt vmcnt(4)
	s_barrier
	global_load_lds_dwordx4 v[8:9], off
	v_lshl_add_u64 v[6:7], v[6:7], 0, s[24:25]
	s_add_i32 m0, s73, 0x1a000
	s_add_i32 s18, s73, 0x8000
	s_add_i32 s19, s73, 0xa000
	v_bitop3_b32 v155, v16, s0, v15 bitop3:0xde
	global_load_lds_dwordx4 v[6:7], off
	v_lshl_add_u64 v[4:5], v[4:5], 0, s[24:25]
	s_mov_b32 m0, s18
	s_add_u32 s0, s62, 0x40080
	global_load_lds_dwordx4 v[4:5], off
	v_lshl_add_u64 v[2:3], v[2:3], 0, s[24:25]
	s_mov_b32 m0, s19
	s_addc_u32 s1, s63, 0
	global_load_lds_dwordx4 v[2:3], off
	s_add_i32 m0, s73, 0x1c000
	v_lshl_add_u64 v[2:3], s[0:1], 0, v[146:147]
	global_load_lds_dwordx4 v[2:3], off
	v_lshl_add_u64 v[2:3], s[0:1], 0, v[148:149]
	s_add_i32 m0, s73, 0x1e000
	v_add_u32_e32 v245, 0x80, v17
	global_load_lds_dwordx4 v[2:3], off
	v_lshlrev_b32_e32 v2, 8, v17
	v_and_b32_e32 v244, 0xcf00, v2
	v_lshlrev_b32_e32 v2, 8, v245
	v_add_u32_e32 v247, 0x90, v17
	v_and_b32_e32 v246, 0xcf00, v2
	v_lshlrev_b32_e32 v2, 8, v247
	v_add_u32_e32 v249, 0xa0, v17
	v_and_b32_e32 v248, 0xdf00, v2
	v_lshlrev_b32_e32 v2, 8, v249
	v_add_u32_e32 v251, 0xb0, v17
	v_and_b32_e32 v250, 0xef00, v2
	v_lshlrev_b32_e32 v2, 8, v251
	v_and_b32_e32 v252, 0xff00, v2
	v_lshlrev_b32_e32 v2, 14, v0
	v_and_b32_e32 v2, 0xffff8000, v2
	v_lshl_add_u32 v2, v10, 11, v2
	v_and_b32_e32 v0, 1, v0
	v_lshl_or_b32 v0, v0, 6, v2
	v_lshl_add_u32 v150, v11, 1, v0
	v_lshlrev_b32_e32 v0, 14, v12
	v_and_b32_e32 v0, 0xffff8000, v0
	s_waitcnt vmcnt(6)
	v_lshl_add_u32 v0, v13, 11, v0
	v_and_b32_e32 v2, 1, v12
	s_add_i32 s0, 0, 0x20000
	v_lshl_or_b32 v0, v2, 6, v0
	v_lshl_add_u32 v179, v18, 2, s0
	s_ashr_i32 s20, s48, 31
	v_lshl_or_b32 v253, s6, 6, v18
	v_mov_b32_e32 v151, v1
	v_lshl_add_u32 v152, v14, 1, v0
	v_mov_b32_e32 v153, v1
	s_mov_b32 s21, 0
	v_add_u32_e32 v231, 0, v19
	s_barrier
	s_cmpk_gt_u32 s8, 0xff
	s_cbranch_scc1 .Lepix_proj
	s_barrier
.Lepix_proj:
	s_branch .LBB0_176
	s_nop 0

.LBB0_178:
	s_ashr_i32 s1, s0, 31
	v_mov_b64_e32 v[2:3], 0x1300
	s_lshl_b64 s[22:23], s[0:1], 19
	v_cmp_lt_i64_e32 vcc, s[84:85], v[2:3]
	s_add_u32 s84, s12, s22
	s_addc_u32 s85, s13, s23
	s_and_b64 s[22:23], vcc, exec
	s_cselect_b32 s1, s85, s3
	s_cselect_b32 s22, s84, s2
	s_ashr_i32 s69, s68, 31
	s_lshl_b64 s[88:89], s[68:69], 19
	s_add_u32 s88, s9, s88
	s_addc_u32 s89, s10, s89
	s_and_b64 s[90:91], vcc, exec
	s_cselect_b32 s23, s89, s63
	s_cselect_b32 s39, s88, s62
	s_add_u32 s2, s2, 0x40080
	s_addc_u32 s3, s3, 0
	s_add_u32 s69, s62, 0x100
	s_addc_u32 vcc_lo, s63, 0
	s_mov_b32 vcc_hi, -2
	s_add_u32 s6, s2, 0xfffc0080
	s_addc_u32 s7, s3, -1
	s_add_i32 s33, 0, 0x10000
	v_add_u32_e32 v0, s33, v155
	ds_read_b128 v[130:133], v0
	ds_read_b128 v[134:137], v0 offset:1024
	ds_read_b128 v[138:141], v0 offset:2048
	ds_read_b128 v[142:145], v0 offset:3072
	s_cmp_eq_u32 vcc_hi, 12
	s_cselect_b32 s91, s1, s7
	s_cselect_b32 s90, s22, s6
	s_cselect_b32 s63, s23, vcc_lo
	s_cselect_b32 s62, s39, s69
	v_lshl_add_u64 v[176:177], s[2:3], 0, v[150:151]
	s_add_i32 m0, s73, 0xc000
	ds_read_b128 v[156:159], v231
	ds_read_b128 v[160:163], v231 offset:1024
	ds_read_b128 v[164:167], v231 offset:2048
	ds_read_b128 v[168:171], v231 offset:3072
	ds_read_b128 v[172:175], v231 offset:4096
	ds_read_b128 v[184:187], v231 offset:5120
	ds_read_b128 v[188:191], v231 offset:6144
	ds_read_b128 v[192:195], v231 offset:7168
	global_load_lds_dwordx4 v[176:177], off
	v_lshl_add_u64 v[176:177], s[2:3], 0, v[152:153]
	s_add_i32 m0, s73, 0xe000
	s_nop 0
	global_load_lds_dwordx4 v[176:177], off
	s_cmpk_gt_u32 s8, 0xff
	s_cbranch_scc0 .Lhbar_proj
	s_barrier
.Lhbar_proj:
	s_waitcnt lgkmcnt(8)
	s_barrier
	s_waitcnt lgkmcnt(0)
	s_waitcnt lgkmcnt(0)
	v_mfma_f32_16x16x32_bf16 v[126:129], v[130:133], v[156:159], 0
	v_mfma_f32_16x16x32_bf16 v[122:125], v[138:141], v[156:159], 0
	v_mfma_f32_16x16x32_bf16 v[110:113], v[130:133], v[164:167], 0
	v_mfma_f32_16x16x32_bf16 v[106:109], v[138:141], v[164:167], 0
	v_mfma_f32_16x16x32_bf16 v[94:97], v[130:133], v[172:175], 0
	v_mfma_f32_16x16x32_bf16 v[90:93], v[138:141], v[172:175], 0
	v_mfma_f32_16x16x32_bf16 v[78:81], v[130:133], v[188:191], 0
	v_mfma_f32_16x16x32_bf16 v[74:77], v[138:141], v[188:191], 0
	v_mfma_f32_16x16x32_bf16 v[126:129], v[134:137], v[160:163], v[126:129]
	v_mfma_f32_16x16x32_bf16 v[122:125], v[142:145], v[160:163], v[122:125]
	v_mfma_f32_16x16x32_bf16 v[110:113], v[134:137], v[168:171], v[110:113]
	v_mfma_f32_16x16x32_bf16 v[106:109], v[142:145], v[168:171], v[106:109]
	v_mfma_f32_16x16x32_bf16 v[94:97], v[134:137], v[184:187], v[94:97]
	v_mfma_f32_16x16x32_bf16 v[90:93], v[142:145], v[184:187], v[90:93]
	v_mfma_f32_16x16x32_bf16 v[78:81], v[134:137], v[192:195], v[78:81]
	v_mfma_f32_16x16x32_bf16 v[74:77], v[142:145], v[192:195], v[74:77]
	s_barrier
	s_add_i32 s94, 0, 0x14000
	s_add_i32 s6, s33, s11
	v_add_u32_e32 v0, s94, v155
	v_lshl_add_u64 v[176:177], s[62:63], 0, v[146:147]
	s_mov_b32 m0, s6
	ds_read_b128 v[196:199], v0
	ds_read_b128 v[200:203], v0 offset:1024
	ds_read_b128 v[204:207], v0 offset:2048
	ds_read_b128 v[208:211], v0 offset:3072
	global_load_lds_dwordx4 v[176:177], off
	v_lshl_add_u64 v[180:181], s[62:63], 0, v[148:149]
	s_add_i32 m0, s6, 0x2000
	s_nop 0
	global_load_lds_dwordx4 v[180:181], off
	s_barrier
	s_waitcnt lgkmcnt(0)
	s_waitcnt lgkmcnt(0)
	v_mfma_f32_16x16x32_bf16 v[118:121], v[196:199], v[156:159], 0
	v_mfma_f32_16x16x32_bf16 v[114:117], v[204:207], v[156:159], 0
	v_mfma_f32_16x16x32_bf16 v[102:105], v[196:199], v[164:167], 0
	v_mfma_f32_16x16x32_bf16 v[98:101], v[204:207], v[164:167], 0
	v_mfma_f32_16x16x32_bf16 v[86:89], v[196:199], v[172:175], 0
	v_mfma_f32_16x16x32_bf16 v[82:85], v[204:207], v[172:175], 0
	v_mfma_f32_16x16x32_bf16 v[70:73], v[196:199], v[188:191], 0
	v_mfma_f32_16x16x32_bf16 v[66:69], v[204:207], v[188:191], 0
	v_mfma_f32_16x16x32_bf16 v[118:121], v[200:203], v[160:163], v[118:121]
	v_mfma_f32_16x16x32_bf16 v[114:117], v[208:211], v[160:163], v[114:117]
	v_mfma_f32_16x16x32_bf16 v[102:105], v[200:203], v[168:171], v[102:105]
	v_mfma_f32_16x16x32_bf16 v[98:101], v[208:211], v[168:171], v[98:101]
	v_mfma_f32_16x16x32_bf16 v[86:89], v[200:203], v[184:187], v[86:89]
	v_mfma_f32_16x16x32_bf16 v[82:85], v[208:211], v[184:187], v[82:85]
	v_mfma_f32_16x16x32_bf16 v[70:73], v[200:203], v[192:195], v[70:73]
	v_mfma_f32_16x16x32_bf16 v[66:69], v[208:211], v[192:195], v[66:69]
	s_mov_b32 m0, s73
	v_lshl_add_u64 v[212:213], s[90:91], 0, v[146:147]
	s_barrier
	ds_read_b128 v[156:159], v231 offset:16384
	ds_read_b128 v[160:163], v231 offset:17408
	ds_read_b128 v[164:167], v231 offset:18432
	ds_read_b128 v[168:171], v231 offset:19456
	ds_read_b128 v[172:175], v231 offset:20480
	ds_read_b128 v[184:187], v231 offset:21504
	ds_read_b128 v[188:191], v231 offset:22528
	ds_read_b128 v[192:195], v231 offset:23552
	global_load_lds_dwordx4 v[212:213], off
	v_lshl_add_u64 v[214:215], s[90:91], 0, v[148:149]
	s_mov_b32 m0, s14
	s_nop 0
	global_load_lds_dwordx4 v[214:215], off
	s_barrier
	s_waitcnt lgkmcnt(0)
	s_waitcnt lgkmcnt(0)
	v_mfma_f32_16x16x32_bf16 v[62:65], v[130:133], v[156:159], 0
	v_mfma_f32_16x16x32_bf16 v[58:61], v[138:141], v[156:159], 0
	v_mfma_f32_16x16x32_bf16 v[46:49], v[130:133], v[164:167], 0
	v_mfma_f32_16x16x32_bf16 v[42:45], v[138:141], v[164:167], 0
	v_mfma_f32_16x16x32_bf16 v[30:33], v[130:133], v[172:175], 0
	v_mfma_f32_16x16x32_bf16 v[26:29], v[138:141], v[172:175], 0
	v_mfma_f32_16x16x32_bf16 v[14:17], v[130:133], v[188:191], 0
	v_mfma_f32_16x16x32_bf16 v[10:13], v[138:141], v[188:191], 0
	v_mfma_f32_16x16x32_bf16 v[62:65], v[134:137], v[160:163], v[62:65]
	v_mfma_f32_16x16x32_bf16 v[58:61], v[142:145], v[160:163], v[58:61]
	v_mfma_f32_16x16x32_bf16 v[46:49], v[134:137], v[168:171], v[46:49]
	v_mfma_f32_16x16x32_bf16 v[42:45], v[142:145], v[168:171], v[42:45]
	v_mfma_f32_16x16x32_bf16 v[30:33], v[134:137], v[184:187], v[30:33]
	v_mfma_f32_16x16x32_bf16 v[26:29], v[142:145], v[184:187], v[26:29]
	v_mfma_f32_16x16x32_bf16 v[14:17], v[134:137], v[192:195], v[14:17]
	v_mfma_f32_16x16x32_bf16 v[10:13], v[142:145], v[192:195], v[10:13]
	s_barrier
	s_add_u32 s6, s62, 0x40000
	s_addc_u32 s7, s63, 0
	s_add_i32 s33, s94, s11
	v_lshl_add_u64 v[130:131], s[6:7], 0, v[146:147]
	s_mov_b32 m0, s33
	s_nop 0
	global_load_lds_dwordx4 v[130:131], off
	v_lshl_add_u64 v[130:131], s[6:7], 0, v[148:149]
	s_add_i32 m0, s33, 0x2000
	s_nop 0
	global_load_lds_dwordx4 v[130:131], off
	s_waitcnt vmcnt(6)
	s_barrier
	v_mfma_f32_16x16x32_bf16 v[54:57], v[196:199], v[156:159], 0
	v_mfma_f32_16x16x32_bf16 v[50:53], v[204:207], v[156:159], 0
	v_mfma_f32_16x16x32_bf16 v[38:41], v[196:199], v[164:167], 0
	v_mfma_f32_16x16x32_bf16 v[34:37], v[204:207], v[164:167], 0
	v_mfma_f32_16x16x32_bf16 v[22:25], v[196:199], v[172:175], 0
	v_mfma_f32_16x16x32_bf16 v[18:21], v[204:207], v[172:175], 0
	v_mfma_f32_16x16x32_bf16 v[6:9], v[196:199], v[188:191], 0
	v_mfma_f32_16x16x32_bf16 v[2:5], v[204:207], v[188:191], 0
	v_mfma_f32_16x16x32_bf16 v[54:57], v[200:203], v[160:163], v[54:57]
	v_mfma_f32_16x16x32_bf16 v[50:53], v[208:211], v[160:163], v[50:53]
	v_mfma_f32_16x16x32_bf16 v[38:41], v[200:203], v[168:171], v[38:41]
	v_mfma_f32_16x16x32_bf16 v[34:37], v[208:211], v[168:171], v[34:37]
	v_mfma_f32_16x16x32_bf16 v[22:25], v[200:203], v[184:187], v[22:25]
	v_mfma_f32_16x16x32_bf16 v[18:21], v[208:211], v[184:187], v[18:21]
	v_mfma_f32_16x16x32_bf16 v[6:9], v[200:203], v[192:195], v[6:9]
	v_mfma_f32_16x16x32_bf16 v[2:5], v[208:211], v[192:195], v[2:5]
	s_add_i32 s33, 0, 0x18000
	v_add_u32_e32 v0, s33, v155
	s_barrier
	ds_read_b128 v[130:133], v0
	ds_read_b128 v[134:137], v0 offset:1024
	ds_read_b128 v[138:141], v0 offset:2048
	ds_read_b128 v[142:145], v0 offset:3072
	s_add_u32 s6, s90, 0x40000
	s_addc_u32 s7, s91, 0
	s_mov_b32 m0, s15
	v_lshl_add_u64 v[196:197], s[6:7], 0, v[146:147]
	ds_read_b128 v[156:159], v231 offset:32768
	ds_read_b128 v[160:163], v231 offset:33792
	ds_read_b128 v[164:167], v231 offset:34816
	ds_read_b128 v[168:171], v231 offset:35840
	ds_read_b128 v[172:175], v231 offset:36864
	ds_read_b128 v[184:187], v231 offset:37888
	ds_read_b128 v[188:191], v231 offset:38912
	ds_read_b128 v[192:195], v231 offset:39936
	global_load_lds_dwordx4 v[196:197], off
	v_lshl_add_u64 v[196:197], s[6:7], 0, v[148:149]
	s_mov_b32 m0, s16
	s_nop 0
	global_load_lds_dwordx4 v[196:197], off
	s_waitcnt lgkmcnt(8)
	s_barrier
	s_waitcnt lgkmcnt(0)
	s_waitcnt lgkmcnt(0)
	v_mfma_f32_16x16x32_bf16 v[126:129], v[130:133], v[156:159], v[126:129]
	v_mfma_f32_16x16x32_bf16 v[122:125], v[138:141], v[156:159], v[122:125]
	v_mfma_f32_16x16x32_bf16 v[110:113], v[130:133], v[164:167], v[110:113]
	v_mfma_f32_16x16x32_bf16 v[106:109], v[138:141], v[164:167], v[106:109]
	v_mfma_f32_16x16x32_bf16 v[94:97], v[130:133], v[172:175], v[94:97]
	v_mfma_f32_16x16x32_bf16 v[90:93], v[138:141], v[172:175], v[90:93]
	v_mfma_f32_16x16x32_bf16 v[78:81], v[130:133], v[188:191], v[78:81]
	v_mfma_f32_16x16x32_bf16 v[74:77], v[138:141], v[188:191], v[74:77]
	v_mfma_f32_16x16x32_bf16 v[126:129], v[134:137], v[160:163], v[126:129]
	v_mfma_f32_16x16x32_bf16 v[122:125], v[142:145], v[160:163], v[122:125]
	v_mfma_f32_16x16x32_bf16 v[110:113], v[134:137], v[168:171], v[110:113]
	v_mfma_f32_16x16x32_bf16 v[106:109], v[142:145], v[168:171], v[106:109]
	v_mfma_f32_16x16x32_bf16 v[94:97], v[134:137], v[184:187], v[94:97]
	v_mfma_f32_16x16x32_bf16 v[90:93], v[142:145], v[184:187], v[90:93]
	v_mfma_f32_16x16x32_bf16 v[78:81], v[134:137], v[192:195], v[78:81]
	v_mfma_f32_16x16x32_bf16 v[74:77], v[142:145], v[192:195], v[74:77]
	s_barrier
	s_add_i32 s90, 0, 0x1c000
	s_add_i32 s6, s33, s11
	v_add_u32_e32 v0, s90, v155
	v_lshl_add_u64 v[176:177], v[176:177], 0, s[24:25]
	s_mov_b32 m0, s6
	ds_read_b128 v[196:199], v0
	ds_read_b128 v[200:203], v0 offset:1024
	ds_read_b128 v[204:207], v0 offset:2048
	ds_read_b128 v[208:211], v0 offset:3072
	global_load_lds_dwordx4 v[176:177], off
	v_lshl_add_u64 v[176:177], v[180:181], 0, s[24:25]
	s_add_i32 m0, s6, 0x2000
	s_nop 0
	global_load_lds_dwordx4 v[176:177], off
	s_barrier
	s_waitcnt lgkmcnt(0)
	s_waitcnt lgkmcnt(0)
	v_mfma_f32_16x16x32_bf16 v[118:121], v[196:199], v[156:159], v[118:121]
	v_mfma_f32_16x16x32_bf16 v[114:117], v[204:207], v[156:159], v[114:117]
	v_mfma_f32_16x16x32_bf16 v[102:105], v[196:199], v[164:167], v[102:105]
	v_mfma_f32_16x16x32_bf16 v[98:101], v[204:207], v[164:167], v[98:101]
	v_mfma_f32_16x16x32_bf16 v[86:89], v[196:199], v[172:175], v[86:89]
	v_mfma_f32_16x16x32_bf16 v[82:85], v[204:207], v[172:175], v[82:85]
	v_mfma_f32_16x16x32_bf16 v[70:73], v[196:199], v[188:191], v[70:73]
	v_mfma_f32_16x16x32_bf16 v[66:69], v[204:207], v[188:191], v[66:69]
	v_mfma_f32_16x16x32_bf16 v[118:121], v[200:203], v[160:163], v[118:121]
	v_mfma_f32_16x16x32_bf16 v[114:117], v[208:211], v[160:163], v[114:117]
	v_mfma_f32_16x16x32_bf16 v[102:105], v[200:203], v[168:171], v[102:105]
	v_mfma_f32_16x16x32_bf16 v[98:101], v[208:211], v[168:171], v[98:101]
	v_mfma_f32_16x16x32_bf16 v[86:89], v[200:203], v[184:187], v[86:89]
	v_mfma_f32_16x16x32_bf16 v[82:85], v[208:211], v[184:187], v[82:85]
	v_mfma_f32_16x16x32_bf16 v[70:73], v[200:203], v[192:195], v[70:73]
	v_mfma_f32_16x16x32_bf16 v[66:69], v[208:211], v[192:195], v[66:69]
	s_mov_b32 m0, s18
	v_lshl_add_u64 v[176:177], v[212:213], 0, s[24:25]
	s_barrier
	ds_read_b128 v[156:159], v231 offset:49152
	ds_read_b128 v[160:163], v231 offset:50176
	ds_read_b128 v[164:167], v231 offset:51200
	ds_read_b128 v[168:171], v231 offset:52224
	ds_read_b128 v[172:175], v231 offset:53248
	ds_read_b128 v[184:187], v231 offset:54272
	ds_read_b128 v[188:191], v231 offset:55296
	ds_read_b128 v[192:195], v231 offset:56320
	global_load_lds_dwordx4 v[176:177], off
	v_lshl_add_u64 v[176:177], v[214:215], 0, s[24:25]
	s_mov_b32 m0, s19
	s_nop 0
	global_load_lds_dwordx4 v[176:177], off
	s_barrier
	s_waitcnt lgkmcnt(0)
	s_waitcnt lgkmcnt(0)
	v_mfma_f32_16x16x32_bf16 v[62:65], v[130:133], v[156:159], v[62:65]
	v_mfma_f32_16x16x32_bf16 v[58:61], v[138:141], v[156:159], v[58:61]
	v_mfma_f32_16x16x32_bf16 v[46:49], v[130:133], v[164:167], v[46:49]
	v_mfma_f32_16x16x32_bf16 v[42:45], v[138:141], v[164:167], v[42:45]
	v_mfma_f32_16x16x32_bf16 v[30:33], v[130:133], v[172:175], v[30:33]
	v_mfma_f32_16x16x32_bf16 v[26:29], v[138:141], v[172:175], v[26:29]
	v_mfma_f32_16x16x32_bf16 v[14:17], v[130:133], v[188:191], v[14:17]
	v_mfma_f32_16x16x32_bf16 v[10:13], v[138:141], v[188:191], v[10:13]
	v_mfma_f32_16x16x32_bf16 v[62:65], v[134:137], v[160:163], v[62:65]
	v_mfma_f32_16x16x32_bf16 v[58:61], v[142:145], v[160:163], v[58:61]
	v_mfma_f32_16x16x32_bf16 v[46:49], v[134:137], v[168:171], v[46:49]
	v_mfma_f32_16x16x32_bf16 v[42:45], v[142:145], v[168:171], v[42:45]
	v_mfma_f32_16x16x32_bf16 v[30:33], v[134:137], v[184:187], v[30:33]
	v_mfma_f32_16x16x32_bf16 v[26:29], v[142:145], v[184:187], v[26:29]
	v_mfma_f32_16x16x32_bf16 v[14:17], v[134:137], v[192:195], v[14:17]
	v_mfma_f32_16x16x32_bf16 v[10:13], v[142:145], v[192:195], v[10:13]
	s_barrier
	s_add_u32 s6, s62, 0x40080
	s_addc_u32 s7, s63, 0
	s_add_i32 s33, s90, s11
	v_lshl_add_u64 v[130:131], s[6:7], 0, v[146:147]
	s_mov_b32 m0, s33
	s_nop 0
	global_load_lds_dwordx4 v[130:131], off
	v_lshl_add_u64 v[130:131], s[6:7], 0, v[148:149]
	s_add_i32 m0, s33, 0x2000
	s_nop 0
	global_load_lds_dwordx4 v[130:131], off
	s_waitcnt vmcnt(6)
	s_barrier
	v_mfma_f32_16x16x32_bf16 v[54:57], v[196:199], v[156:159], v[54:57]
	v_mfma_f32_16x16x32_bf16 v[50:53], v[204:207], v[156:159], v[50:53]
	v_mfma_f32_16x16x32_bf16 v[38:41], v[196:199], v[164:167], v[38:41]
	v_mfma_f32_16x16x32_bf16 v[34:37], v[204:207], v[164:167], v[34:37]
	v_mfma_f32_16x16x32_bf16 v[22:25], v[196:199], v[172:175], v[22:25]
	v_mfma_f32_16x16x32_bf16 v[18:21], v[204:207], v[172:175], v[18:21]
	v_mfma_f32_16x16x32_bf16 v[6:9], v[196:199], v[188:191], v[6:9]
	v_mfma_f32_16x16x32_bf16 v[2:5], v[204:207], v[188:191], v[2:5]
	v_mfma_f32_16x16x32_bf16 v[54:57], v[200:203], v[160:163], v[54:57]
	v_mfma_f32_16x16x32_bf16 v[50:53], v[208:211], v[160:163], v[50:53]
	v_mfma_f32_16x16x32_bf16 v[38:41], v[200:203], v[168:171], v[38:41]
	v_mfma_f32_16x16x32_bf16 v[34:37], v[208:211], v[168:171], v[34:37]
	v_mfma_f32_16x16x32_bf16 v[22:25], v[200:203], v[184:187], v[22:25]
	v_mfma_f32_16x16x32_bf16 v[18:21], v[208:211], v[184:187], v[18:21]
	v_mfma_f32_16x16x32_bf16 v[6:9], v[200:203], v[192:195], v[6:9]
	v_mfma_f32_16x16x32_bf16 v[2:5], v[208:211], v[192:195], v[2:5]
	s_add_i32 vcc_hi, vcc_hi, 2
	s_add_u32 s2, s2, 0x100
	s_addc_u32 s3, s3, 0
	s_add_u32 s69, s69, 0x100
	s_addc_u32 vcc_lo, vcc_lo, 0
	s_cmp_gt_u32 vcc_hi, 13
	s_barrier

.LBB0_272:
	s_waitcnt vmcnt(0)
	s_cmpk_gt_u32 s8, 0xff
	v_readlane_b32 s13, v255, 30
	v_and_b32_e32 v228, 63, v230
	v_mov_b32_e32 v246, 0x42000000
	v_not_b32_e32 v247, 25
	v_mov_b64_e32 v[248:249], 0x1ff
	s_cbranch_scc1 .LBB0_274
.LBB0_274:
	v_readlane_b32 s28, v255, 31
	v_mov_b32_e32 v231, 1
	s_barrier
	s_or_b32 s8, s13, 3
	s_cmp_ge_i32 s8, s83
	s_cbranch_scc1 .LBB0_328

.LBB0_519:
	s_lshl_b32 s0, s28, 26
	s_add_u32 s0, s18, s0
	s_addc_u32 s1, s19, 0
	s_add_u32 s0, s0, 0x3c00000
	v_lshrrev_b32_e32 v17, 1, v13
	s_addc_u32 s1, s1, 0
	v_and_b32_e32 v17, 24, v17
	s_add_u32 s40, s18, 0x19c00000
	v_and_b32_e32 v16, 15, v13
	v_lshlrev_b32_e32 v18, 1, v17
	v_lshlrev_b32_e32 v13, 2, v13
	s_addc_u32 s41, s19, 0
	s_and_b32 s6, s20, 3
	v_lshl_or_b32 v179, s21, 6, v16
	v_lshl_or_b32 v16, v16, 6, v18
	s_lshl_b32 s7, s21, 13
	v_and_b32_e32 v13, 32, v13
	v_bitop3_b32 v18, v16, s7, v13 bitop3:0xde
	s_lshl_b32 s7, s6, 12
	s_add_i32 m0, s3, 0x18000
	v_lshl_add_u64 v[8:9], v[8:9], 0, s[24:25]
	v_bitop3_b32 v184, v16, s7, v13 bitop3:0xde
	s_waitcnt vmcnt(4)
	s_barrier
	global_load_lds_dwordx4 v[8:9], off
	v_lshl_add_u64 v[6:7], v[6:7], 0, s[24:25]
	s_add_i32 m0, s3, 0x1a000
	s_add_i32 s7, s3, 0x8000
	s_add_i32 s18, s3, 0xa000
	global_load_lds_dwordx4 v[6:7], off
	v_lshl_add_u64 v[4:5], v[4:5], 0, s[24:25]
	s_mov_b32 m0, s7
	s_add_u32 s20, s90, 0x20080
	global_load_lds_dwordx4 v[4:5], off
	v_lshl_add_u64 v[2:3], v[2:3], 0, s[24:25]
	s_mov_b32 m0, s18
	s_addc_u32 s21, s91, 0
	global_load_lds_dwordx4 v[2:3], off
	s_add_i32 m0, s3, 0x1c000
	v_lshl_add_u64 v[2:3], s[20:21], 0, v[162:163]
	global_load_lds_dwordx4 v[2:3], off
	v_lshl_add_u64 v[2:3], s[20:21], 0, v[164:165]
	s_add_i32 m0, s3, 0x1e000
	v_or_b32_e32 v186, 16, v179
	global_load_lds_dwordx4 v[2:3], off
	v_lshlrev_b32_e32 v2, 8, v179
	v_and_b32_e32 v185, 0xcf00, v2
	v_lshlrev_b32_e32 v2, 8, v186
	v_or_b32_e32 v188, 32, v179
	v_and_b32_e32 v187, 0xdf00, v2
	v_lshlrev_b32_e32 v2, 8, v188
	v_or_b32_e32 v190, 48, v179
	v_and_b32_e32 v189, 0xef00, v2
	v_lshlrev_b32_e32 v2, 8, v190
	v_add_u32_e32 v192, 0x80, v179
	v_and_b32_e32 v191, 0xff00, v2
	v_lshlrev_b32_e32 v2, 8, v192
	v_add_u32_e32 v194, 0x90, v179
	v_and_b32_e32 v193, 0xcf00, v2
	v_lshlrev_b32_e32 v2, 8, v194
	v_add_u32_e32 v196, 0xa0, v179
	v_and_b32_e32 v195, 0xdf00, v2
	v_lshlrev_b32_e32 v2, 8, v196
	v_add_u32_e32 v198, 0xb0, v179
	v_and_b32_e32 v197, 0xef00, v2
	v_lshlrev_b32_e32 v2, 8, v198
	v_and_b32_e32 v199, 0xff00, v2
	v_lshlrev_b32_e32 v2, 13, v0
	v_and_b32_e32 v2, 0xffffc000, v2
	v_lshl_add_u32 v2, v10, 10, v2
	v_and_b32_e32 v0, 1, v0
	v_lshl_or_b32 v0, v0, 6, v2
	v_lshl_add_u32 v166, v11, 1, v0
	v_lshlrev_b32_e32 v0, 13, v12
	v_and_b32_e32 v0, 0xffffc000, v0
	s_waitcnt vmcnt(6)
	v_lshl_add_u32 v0, v14, 10, v0
	v_and_b32_e32 v2, 1, v12
	v_lshl_or_b32 v0, v2, 6, v0
	s_ashr_i32 s19, s8, 31
	v_lshl_or_b32 v200, s6, 6, v17
	v_mov_b32_e32 v167, v1
	v_lshl_add_u32 v168, v15, 1, v0
	v_mov_b32_e32 v169, v1
	s_mov_b32 s20, 0
	v_add_u32_e32 v201, 0, v18
	s_barrier
	s_cmpk_gt_u32 s9, 0xff
	s_cbranch_scc1 .Lepix_branch
	s_barrier
.Lepix_branch:
	s_branch .LBB0_521
	s_nop 0
	s_nop 0
	s_nop 0
	s_nop 0
	s_nop 0
	s_nop 0
	s_nop 0
	s_nop 0
	s_nop 0
	s_nop 0
	s_nop 0
	s_nop 0
	s_nop 0
	s_nop 0

.LBB0_527:
	s_ashr_i32 s47, s46, 31
	s_lshl_b64 s[22:23], s[46:47], 18
	v_cmp_lt_i64_e32 vcc, s[84:85], v[182:183]
	s_add_u32 s84, s10, s22
	s_addc_u32 s85, s11, s23
	s_and_b64 s[22:23], vcc, exec
	s_cselect_b32 s21, s85, s63
	s_cselect_b32 s22, s84, s62
	s_ashr_i32 s69, s68, 31
	s_lshl_b64 s[72:73], s[68:69], 18
	s_add_u32 s88, s12, s72
	s_addc_u32 s89, s13, s73
	s_and_b64 s[72:73], vcc, exec
	s_cselect_b32 s23, s89, s91
	s_cselect_b32 s39, s88, s90
	s_add_u32 s62, s62, 0x20080
	s_addc_u32 s63, s63, 0
	s_add_u32 s47, s90, 0x100
	s_addc_u32 s48, s91, 0
	s_mov_b32 s69, -2
	s_add_u32 s6, s62, 0xfffe0080
	s_addc_u32 s33, s63, -1
	s_add_i32 s72, 0, 0x10000
	v_add_u32_e32 v0, s72, v184
	ds_read_b128 v[130:133], v0
	ds_read_b128 v[134:137], v0 offset:1024
	ds_read_b128 v[138:141], v0 offset:2048
	ds_read_b128 v[142:145], v0 offset:3072
	s_cmp_eq_u32 s69, 4
	s_cselect_b32 vcc_hi, s21, s33
	s_cselect_b32 vcc_lo, s22, s6
	s_cselect_b32 s91, s23, s48
	s_cselect_b32 s90, s39, s47
	v_lshl_add_u64 v[180:181], s[62:63], 0, v[166:167]
	s_add_i32 m0, s3, 0xc000
	ds_read_b128 v[146:149], v201
	ds_read_b128 v[150:153], v201 offset:1024
	ds_read_b128 v[154:157], v201 offset:2048
	ds_read_b128 v[158:161], v201 offset:3072
	ds_read_b128 v[170:173], v201 offset:4096
	ds_read_b128 v[174:177], v201 offset:5120
	ds_read_b128 v[202:205], v201 offset:6144
	ds_read_b128 v[206:209], v201 offset:7168
	global_load_lds_dwordx4 v[180:181], off
	v_lshl_add_u64 v[180:181], s[62:63], 0, v[168:169]
	s_add_i32 m0, s3, 0xe000
	s_nop 0
	global_load_lds_dwordx4 v[180:181], off
	s_cmpk_gt_u32 s9, 0xff
	s_cbranch_scc0 .Lhbar_branch
	s_barrier
.Lhbar_branch:
	s_waitcnt lgkmcnt(8)
	s_barrier
	s_waitcnt lgkmcnt(0)
	s_waitcnt lgkmcnt(0)
	v_mfma_f32_16x16x32_bf16 v[126:129], v[130:133], v[146:149], 0
	v_mfma_f32_16x16x32_bf16 v[122:125], v[138:141], v[146:149], 0
	v_mfma_f32_16x16x32_bf16 v[110:113], v[130:133], v[154:157], 0
	v_mfma_f32_16x16x32_bf16 v[106:109], v[138:141], v[154:157], 0
	v_mfma_f32_16x16x32_bf16 v[94:97], v[130:133], v[170:173], 0
	v_mfma_f32_16x16x32_bf16 v[90:93], v[138:141], v[170:173], 0
	v_mfma_f32_16x16x32_bf16 v[78:81], v[130:133], v[202:205], 0
	v_mfma_f32_16x16x32_bf16 v[74:77], v[138:141], v[202:205], 0
	v_mfma_f32_16x16x32_bf16 v[126:129], v[134:137], v[150:153], v[126:129]
	v_mfma_f32_16x16x32_bf16 v[122:125], v[142:145], v[150:153], v[122:125]
	v_mfma_f32_16x16x32_bf16 v[110:113], v[134:137], v[158:161], v[110:113]
	v_mfma_f32_16x16x32_bf16 v[106:109], v[142:145], v[158:161], v[106:109]
	v_mfma_f32_16x16x32_bf16 v[94:97], v[134:137], v[174:177], v[94:97]
	v_mfma_f32_16x16x32_bf16 v[90:93], v[142:145], v[174:177], v[90:93]
	v_mfma_f32_16x16x32_bf16 v[78:81], v[134:137], v[206:209], v[78:81]
	v_mfma_f32_16x16x32_bf16 v[74:77], v[142:145], v[206:209], v[74:77]
	s_barrier
	s_add_i32 s6, 0, 0x14000
	s_add_i32 s33, s72, s14
	v_add_u32_e32 v0, s6, v184
	v_lshl_add_u64 v[180:181], s[90:91], 0, v[162:163]
	s_mov_b32 m0, s33
	ds_read_b128 v[210:213], v0
	ds_read_b128 v[214:217], v0 offset:1024
	ds_read_b128 v[218:221], v0 offset:2048
	ds_read_b128 v[222:225], v0 offset:3072
	global_load_lds_dwordx4 v[180:181], off
	v_lshl_add_u64 v[226:227], s[90:91], 0, v[164:165]
	s_add_i32 m0, s33, 0x2000
	s_nop 0
	global_load_lds_dwordx4 v[226:227], off
	s_barrier
	s_waitcnt lgkmcnt(0)
	s_waitcnt lgkmcnt(0)
	v_mfma_f32_16x16x32_bf16 v[118:121], v[210:213], v[146:149], 0
	v_mfma_f32_16x16x32_bf16 v[114:117], v[218:221], v[146:149], 0
	v_mfma_f32_16x16x32_bf16 v[102:105], v[210:213], v[154:157], 0
	v_mfma_f32_16x16x32_bf16 v[98:101], v[218:221], v[154:157], 0
	v_mfma_f32_16x16x32_bf16 v[86:89], v[210:213], v[170:173], 0
	v_mfma_f32_16x16x32_bf16 v[82:85], v[218:221], v[170:173], 0
	v_mfma_f32_16x16x32_bf16 v[70:73], v[210:213], v[202:205], 0
	v_mfma_f32_16x16x32_bf16 v[66:69], v[218:221], v[202:205], 0
	v_mfma_f32_16x16x32_bf16 v[118:121], v[214:217], v[150:153], v[118:121]
	v_mfma_f32_16x16x32_bf16 v[114:117], v[222:225], v[150:153], v[114:117]
	v_mfma_f32_16x16x32_bf16 v[102:105], v[214:217], v[158:161], v[102:105]
	v_mfma_f32_16x16x32_bf16 v[98:101], v[222:225], v[158:161], v[98:101]
	v_mfma_f32_16x16x32_bf16 v[86:89], v[214:217], v[174:177], v[86:89]
	v_mfma_f32_16x16x32_bf16 v[82:85], v[222:225], v[174:177], v[82:85]
	v_mfma_f32_16x16x32_bf16 v[70:73], v[214:217], v[206:209], v[70:73]
	v_mfma_f32_16x16x32_bf16 v[66:69], v[222:225], v[206:209], v[66:69]
	s_mov_b32 m0, s3
	v_lshl_add_u64 v[240:241], vcc, 0, v[162:163]
	s_barrier
	ds_read_b128 v[146:149], v201 offset:16384
	ds_read_b128 v[150:153], v201 offset:17408
	ds_read_b128 v[154:157], v201 offset:18432
	ds_read_b128 v[158:161], v201 offset:19456
	ds_read_b128 v[170:173], v201 offset:20480
	ds_read_b128 v[174:177], v201 offset:21504
	ds_read_b128 v[202:205], v201 offset:22528
	ds_read_b128 v[206:209], v201 offset:23552
	global_load_lds_dwordx4 v[240:241], off
	v_lshl_add_u64 v[244:245], vcc, 0, v[164:165]
	s_mov_b32 m0, s15
	s_nop 0
	global_load_lds_dwordx4 v[244:245], off
	s_barrier
	s_waitcnt lgkmcnt(0)
	s_waitcnt lgkmcnt(0)
	v_mfma_f32_16x16x32_bf16 v[62:65], v[130:133], v[146:149], 0
	v_mfma_f32_16x16x32_bf16 v[58:61], v[138:141], v[146:149], 0
	v_mfma_f32_16x16x32_bf16 v[46:49], v[130:133], v[154:157], 0
	v_mfma_f32_16x16x32_bf16 v[42:45], v[138:141], v[154:157], 0
	v_mfma_f32_16x16x32_bf16 v[30:33], v[130:133], v[170:173], 0
	v_mfma_f32_16x16x32_bf16 v[26:29], v[138:141], v[170:173], 0
	v_mfma_f32_16x16x32_bf16 v[14:17], v[130:133], v[202:205], 0
	v_mfma_f32_16x16x32_bf16 v[10:13], v[138:141], v[202:205], 0
	v_mfma_f32_16x16x32_bf16 v[62:65], v[134:137], v[150:153], v[62:65]
	v_mfma_f32_16x16x32_bf16 v[58:61], v[142:145], v[150:153], v[58:61]
	v_mfma_f32_16x16x32_bf16 v[46:49], v[134:137], v[158:161], v[46:49]
	v_mfma_f32_16x16x32_bf16 v[42:45], v[142:145], v[158:161], v[42:45]
	v_mfma_f32_16x16x32_bf16 v[30:33], v[134:137], v[174:177], v[30:33]
	v_mfma_f32_16x16x32_bf16 v[26:29], v[142:145], v[174:177], v[26:29]
	v_mfma_f32_16x16x32_bf16 v[14:17], v[134:137], v[206:209], v[14:17]
	v_mfma_f32_16x16x32_bf16 v[10:13], v[142:145], v[206:209], v[10:13]
	s_barrier
	s_add_u32 s72, s90, 0x20000
	s_addc_u32 s73, s91, 0
	s_add_i32 s6, s6, s14
	v_lshl_add_u64 v[130:131], s[72:73], 0, v[162:163]
	s_mov_b32 m0, s6
	s_nop 0
	global_load_lds_dwordx4 v[130:131], off
	v_lshl_add_u64 v[130:131], s[72:73], 0, v[164:165]
	s_add_i32 m0, s6, 0x2000
	s_nop 0
	global_load_lds_dwordx4 v[130:131], off
	s_waitcnt vmcnt(6)
	s_barrier
	v_mfma_f32_16x16x32_bf16 v[54:57], v[210:213], v[146:149], 0
	v_mfma_f32_16x16x32_bf16 v[50:53], v[218:221], v[146:149], 0
	v_mfma_f32_16x16x32_bf16 v[38:41], v[210:213], v[154:157], 0
	v_mfma_f32_16x16x32_bf16 v[34:37], v[218:221], v[154:157], 0
	v_mfma_f32_16x16x32_bf16 v[22:25], v[210:213], v[170:173], 0
	v_mfma_f32_16x16x32_bf16 v[18:21], v[218:221], v[170:173], 0
	v_mfma_f32_16x16x32_bf16 v[6:9], v[210:213], v[202:205], 0
	v_mfma_f32_16x16x32_bf16 v[2:5], v[218:221], v[202:205], 0
	v_mfma_f32_16x16x32_bf16 v[54:57], v[214:217], v[150:153], v[54:57]
	v_mfma_f32_16x16x32_bf16 v[50:53], v[222:225], v[150:153], v[50:53]
	v_mfma_f32_16x16x32_bf16 v[38:41], v[214:217], v[158:161], v[38:41]
	v_mfma_f32_16x16x32_bf16 v[34:37], v[222:225], v[158:161], v[34:37]
	v_mfma_f32_16x16x32_bf16 v[22:25], v[214:217], v[174:177], v[22:25]
	v_mfma_f32_16x16x32_bf16 v[18:21], v[222:225], v[174:177], v[18:21]
	v_mfma_f32_16x16x32_bf16 v[6:9], v[214:217], v[206:209], v[6:9]
	v_mfma_f32_16x16x32_bf16 v[2:5], v[222:225], v[206:209], v[2:5]
	s_add_i32 s6, 0, 0x18000
	v_add_u32_e32 v0, s6, v184
	s_barrier
	ds_read_b128 v[130:133], v0
	ds_read_b128 v[134:137], v0 offset:1024
	ds_read_b128 v[138:141], v0 offset:2048
	ds_read_b128 v[142:145], v0 offset:3072
	s_add_u32 s72, vcc_lo, 0x20000
	s_addc_u32 s73, vcc_hi, 0
	s_mov_b32 m0, s16
	v_lshl_add_u64 v[210:211], s[72:73], 0, v[162:163]
	ds_read_b128 v[146:149], v201 offset:32768
	ds_read_b128 v[150:153], v201 offset:33792
	ds_read_b128 v[154:157], v201 offset:34816
	ds_read_b128 v[158:161], v201 offset:35840
	ds_read_b128 v[170:173], v201 offset:36864
	ds_read_b128 v[174:177], v201 offset:37888
	ds_read_b128 v[202:205], v201 offset:38912
	ds_read_b128 v[206:209], v201 offset:39936
	global_load_lds_dwordx4 v[210:211], off
	v_lshl_add_u64 v[210:211], s[72:73], 0, v[164:165]
	s_mov_b32 m0, s17
	s_nop 0
	global_load_lds_dwordx4 v[210:211], off
	s_waitcnt lgkmcnt(8)
	s_barrier
	s_waitcnt lgkmcnt(0)
	s_waitcnt lgkmcnt(0)
	v_mfma_f32_16x16x32_bf16 v[126:129], v[130:133], v[146:149], v[126:129]
	v_mfma_f32_16x16x32_bf16 v[122:125], v[138:141], v[146:149], v[122:125]
	v_mfma_f32_16x16x32_bf16 v[110:113], v[130:133], v[154:157], v[110:113]
	v_mfma_f32_16x16x32_bf16 v[106:109], v[138:141], v[154:157], v[106:109]
	v_mfma_f32_16x16x32_bf16 v[94:97], v[130:133], v[170:173], v[94:97]
	v_mfma_f32_16x16x32_bf16 v[90:93], v[138:141], v[170:173], v[90:93]
	v_mfma_f32_16x16x32_bf16 v[78:81], v[130:133], v[202:205], v[78:81]
	v_mfma_f32_16x16x32_bf16 v[74:77], v[138:141], v[202:205], v[74:77]
	v_mfma_f32_16x16x32_bf16 v[126:129], v[134:137], v[150:153], v[126:129]
	v_mfma_f32_16x16x32_bf16 v[122:125], v[142:145], v[150:153], v[122:125]
	v_mfma_f32_16x16x32_bf16 v[110:113], v[134:137], v[158:161], v[110:113]
	v_mfma_f32_16x16x32_bf16 v[106:109], v[142:145], v[158:161], v[106:109]
	v_mfma_f32_16x16x32_bf16 v[94:97], v[134:137], v[174:177], v[94:97]
	v_mfma_f32_16x16x32_bf16 v[90:93], v[142:145], v[174:177], v[90:93]
	v_mfma_f32_16x16x32_bf16 v[78:81], v[134:137], v[206:209], v[78:81]
	v_mfma_f32_16x16x32_bf16 v[74:77], v[142:145], v[206:209], v[74:77]
	s_barrier
	s_add_i32 s33, 0, 0x1c000
	s_add_i32 s6, s6, s14
	v_add_u32_e32 v0, s33, v184
	v_lshl_add_u64 v[180:181], v[180:181], 0, s[24:25]
	s_mov_b32 m0, s6
	ds_read_b128 v[210:213], v0
	ds_read_b128 v[214:217], v0 offset:1024
	ds_read_b128 v[218:221], v0 offset:2048
	ds_read_b128 v[222:225], v0 offset:3072
	global_load_lds_dwordx4 v[180:181], off
	v_lshl_add_u64 v[180:181], v[226:227], 0, s[24:25]
	s_add_i32 m0, s6, 0x2000
	s_nop 0
	global_load_lds_dwordx4 v[180:181], off
	s_barrier
	s_waitcnt lgkmcnt(0)
	s_waitcnt lgkmcnt(0)
	v_mfma_f32_16x16x32_bf16 v[118:121], v[210:213], v[146:149], v[118:121]
	v_mfma_f32_16x16x32_bf16 v[114:117], v[218:221], v[146:149], v[114:117]
	v_mfma_f32_16x16x32_bf16 v[102:105], v[210:213], v[154:157], v[102:105]
	v_mfma_f32_16x16x32_bf16 v[98:101], v[218:221], v[154:157], v[98:101]
	v_mfma_f32_16x16x32_bf16 v[86:89], v[210:213], v[170:173], v[86:89]
	v_mfma_f32_16x16x32_bf16 v[82:85], v[218:221], v[170:173], v[82:85]
	v_mfma_f32_16x16x32_bf16 v[70:73], v[210:213], v[202:205], v[70:73]
	v_mfma_f32_16x16x32_bf16 v[66:69], v[218:221], v[202:205], v[66:69]
	v_mfma_f32_16x16x32_bf16 v[118:121], v[214:217], v[150:153], v[118:121]
	v_mfma_f32_16x16x32_bf16 v[114:117], v[222:225], v[150:153], v[114:117]
	v_mfma_f32_16x16x32_bf16 v[102:105], v[214:217], v[158:161], v[102:105]
	v_mfma_f32_16x16x32_bf16 v[98:101], v[222:225], v[158:161], v[98:101]
	v_mfma_f32_16x16x32_bf16 v[86:89], v[214:217], v[174:177], v[86:89]
	v_mfma_f32_16x16x32_bf16 v[82:85], v[222:225], v[174:177], v[82:85]
	v_mfma_f32_16x16x32_bf16 v[70:73], v[214:217], v[206:209], v[70:73]
	v_mfma_f32_16x16x32_bf16 v[66:69], v[222:225], v[206:209], v[66:69]
	s_mov_b32 m0, s7
	v_lshl_add_u64 v[180:181], v[240:241], 0, s[24:25]
	s_barrier
	ds_read_b128 v[146:149], v201 offset:49152
	ds_read_b128 v[150:153], v201 offset:50176
	ds_read_b128 v[154:157], v201 offset:51200
	ds_read_b128 v[158:161], v201 offset:52224
	ds_read_b128 v[170:173], v201 offset:53248
	ds_read_b128 v[174:177], v201 offset:54272
	ds_read_b128 v[202:205], v201 offset:55296
	ds_read_b128 v[206:209], v201 offset:56320
	global_load_lds_dwordx4 v[180:181], off
	v_lshl_add_u64 v[180:181], v[244:245], 0, s[24:25]
	s_mov_b32 m0, s18
	s_nop 0
	global_load_lds_dwordx4 v[180:181], off
	s_barrier
	s_waitcnt lgkmcnt(0)
	s_waitcnt lgkmcnt(0)
	v_mfma_f32_16x16x32_bf16 v[62:65], v[130:133], v[146:149], v[62:65]
	v_mfma_f32_16x16x32_bf16 v[58:61], v[138:141], v[146:149], v[58:61]
	v_mfma_f32_16x16x32_bf16 v[46:49], v[130:133], v[154:157], v[46:49]
	v_mfma_f32_16x16x32_bf16 v[42:45], v[138:141], v[154:157], v[42:45]
	v_mfma_f32_16x16x32_bf16 v[30:33], v[130:133], v[170:173], v[30:33]
	v_mfma_f32_16x16x32_bf16 v[26:29], v[138:141], v[170:173], v[26:29]
	v_mfma_f32_16x16x32_bf16 v[14:17], v[130:133], v[202:205], v[14:17]
	v_mfma_f32_16x16x32_bf16 v[10:13], v[138:141], v[202:205], v[10:13]
	v_mfma_f32_16x16x32_bf16 v[62:65], v[134:137], v[150:153], v[62:65]
	v_mfma_f32_16x16x32_bf16 v[58:61], v[142:145], v[150:153], v[58:61]
	v_mfma_f32_16x16x32_bf16 v[46:49], v[134:137], v[158:161], v[46:49]
	v_mfma_f32_16x16x32_bf16 v[42:45], v[142:145], v[158:161], v[42:45]
	v_mfma_f32_16x16x32_bf16 v[30:33], v[134:137], v[174:177], v[30:33]
	v_mfma_f32_16x16x32_bf16 v[26:29], v[142:145], v[174:177], v[26:29]
	v_mfma_f32_16x16x32_bf16 v[14:17], v[134:137], v[206:209], v[14:17]
	v_mfma_f32_16x16x32_bf16 v[10:13], v[142:145], v[206:209], v[10:13]
	s_barrier
	s_add_u32 s72, s90, 0x20080
	s_addc_u32 s73, s91, 0
	s_add_i32 s6, s33, s14
	v_lshl_add_u64 v[130:131], s[72:73], 0, v[162:163]
	s_mov_b32 m0, s6
	s_nop 0
	global_load_lds_dwordx4 v[130:131], off
	v_lshl_add_u64 v[130:131], s[72:73], 0, v[164:165]
	s_add_i32 m0, s6, 0x2000
	s_nop 0
	global_load_lds_dwordx4 v[130:131], off
	s_waitcnt vmcnt(6)
	s_barrier
	v_mfma_f32_16x16x32_bf16 v[54:57], v[210:213], v[146:149], v[54:57]
	v_mfma_f32_16x16x32_bf16 v[50:53], v[218:221], v[146:149], v[50:53]
	v_mfma_f32_16x16x32_bf16 v[38:41], v[210:213], v[154:157], v[38:41]
	v_mfma_f32_16x16x32_bf16 v[34:37], v[218:221], v[154:157], v[34:37]
	v_mfma_f32_16x16x32_bf16 v[22:25], v[210:213], v[170:173], v[22:25]
	v_mfma_f32_16x16x32_bf16 v[18:21], v[218:221], v[170:173], v[18:21]
	v_mfma_f32_16x16x32_bf16 v[6:9], v[210:213], v[202:205], v[6:9]
	v_mfma_f32_16x16x32_bf16 v[2:5], v[218:221], v[202:205], v[2:5]
	v_mfma_f32_16x16x32_bf16 v[54:57], v[214:217], v[150:153], v[54:57]
	v_mfma_f32_16x16x32_bf16 v[50:53], v[222:225], v[150:153], v[50:53]
	v_mfma_f32_16x16x32_bf16 v[38:41], v[214:217], v[158:161], v[38:41]
	v_mfma_f32_16x16x32_bf16 v[34:37], v[222:225], v[158:161], v[34:37]
	v_mfma_f32_16x16x32_bf16 v[22:25], v[214:217], v[174:177], v[22:25]
	v_mfma_f32_16x16x32_bf16 v[18:21], v[222:225], v[174:177], v[18:21]
	v_mfma_f32_16x16x32_bf16 v[6:9], v[214:217], v[206:209], v[6:9]
	v_mfma_f32_16x16x32_bf16 v[2:5], v[222:225], v[206:209], v[2:5]
	s_add_i32 s69, s69, 2
	s_add_u32 s62, s62, 0x100
	s_addc_u32 s63, s63, 0
	s_add_u32 s47, s47, 0x100
	s_addc_u32 s48, s48, 0
	s_cmp_gt_u32 s69, 5
	s_barrier

.LBB0_545:
	s_waitcnt vmcnt(0)
	s_cmpk_gt_u32 s9, 0xff
	v_readlane_b32 s13, v255, 30
	s_cbranch_scc1 .LBB0_547
.LBB0_547:
	s_barrier
	s_add_i32 s0, s13, 6
	s_cmp_ge_i32 s0, s83
	s_cbranch_scc1 .LBB0_162

.LBB0_609:
	s_add_u32 s24, s16, 0x19c00000
	s_addc_u32 s25, s17, 0
	v_bfe_u32 v16, v8, 4, 2
	s_add_u32 s26, s16, 0x12000000
	v_and_b32_e32 v15, 15, v8
	v_lshlrev_b32_e32 v18, 4, v16
	v_lshlrev_b32_e32 v8, 2, v8
	s_addc_u32 s27, s17, 0
	s_and_b32 s3, s18, 3
	v_lshl_or_b32 v182, s19, 6, v15
	v_lshl_or_b32 v15, v15, 6, v18
	s_lshl_b32 s16, s19, 13
	v_and_b32_e32 v8, 32, v8
	s_mov_b64 s[28:29], 0x80
	v_bitop3_b32 v18, v15, s16, v8 bitop3:0xde
	s_lshl_b32 s16, s3, 12
	s_add_i32 m0, s11, 0x18000
	v_lshl_add_u64 v[6:7], v[6:7], 0, s[28:29]
	v_bitop3_b32 v183, v15, s16, v8 bitop3:0xde
	s_waitcnt vmcnt(4)
	s_barrier
	global_load_lds_dwordx4 v[6:7], off
	v_lshl_add_u64 v[4:5], v[4:5], 0, s[28:29]
	s_add_i32 m0, s11, 0x1a000
	s_add_i32 s16, s11, 0x8000
	s_add_i32 s17, s11, 0xa000
	global_load_lds_dwordx4 v[4:5], off
	v_lshl_add_u64 v[2:3], v[2:3], 0, s[28:29]
	s_mov_b32 m0, s16
	s_add_u32 s18, s52, 0x40080
	global_load_lds_dwordx4 v[2:3], off
	v_lshl_add_u64 v[0:1], v[0:1], 0, s[28:29]
	s_mov_b32 m0, s17
	s_addc_u32 s19, s53, 0
	global_load_lds_dwordx4 v[0:1], off
	s_add_i32 m0, s11, 0x1c000
	v_lshl_add_u64 v[0:1], s[18:19], 0, v[160:161]
	global_load_lds_dwordx4 v[0:1], off
	v_lshl_add_u64 v[0:1], s[18:19], 0, v[162:163]
	s_add_i32 m0, s11, 0x1e000
	v_lshlrev_b32_e32 v17, 3, v16
	global_load_lds_dwordx4 v[0:1], off
	v_lshlrev_b32_e32 v0, 14, v9
	v_and_b32_e32 v0, 0xffff8000, v0
	v_lshl_add_u32 v0, v10, 11, v0
	v_and_b32_e32 v1, 1, v9
	v_lshl_or_b32 v0, v1, 6, v0
	v_lshl_add_u32 v164, v11, 1, v0
	v_lshlrev_b32_e32 v0, 14, v12
	v_and_b32_e32 v0, 0xffff8000, v0
	s_waitcnt vmcnt(6)
	v_lshl_add_u32 v0, v13, 11, v0
	v_and_b32_e32 v1, 1, v12
	v_lshl_or_b32 v0, v1, 6, v0
	s_add_i32 s19, 0, 0x10000
	s_add_i32 s20, 0, 0x14000
	v_lshl_or_b32 v184, s3, 6, v17
	v_cmp_eq_u32_e64 s[36:37], 0, v16
	s_ashr_i32 s18, s4, 31
	v_mov_b32_e32 v165, v161
	v_lshl_add_u32 v166, v14, 1, v0
	v_mov_b32_e32 v167, v161
	v_mov_b64_e32 v[168:169], 0x400
	v_mov_b64_e32 v[170:171], 0x3ff
	v_add_u32_e32 v185, s19, v183
	v_add_u32_e32 v186, 0, v18
	v_add_u32_e32 v187, s20, v183
	s_barrier
	s_cmpk_gt_u32 s5, 0xff
	s_cbranch_scc1 .Lepix_out
	s_barrier
.Lepix_out:
	s_branch .LBB0_611
	s_nop 0
	s_nop 0
	s_nop 0
	s_nop 0
	s_nop 0

.LBB0_617:
	s_ashr_i32 s31, s30, 31
	s_lshl_b64 s[22:23], s[30:31], 19
	v_cmp_lt_i64_e32 vcc, s[40:41], v[168:169]
	s_add_u32 s40, s6, s22
	s_addc_u32 s41, s7, s23
	s_and_b64 s[22:23], vcc, exec
	s_cselect_b32 s3, s41, s49
	s_cselect_b32 s21, s40, s48
	s_ashr_i32 s35, s34, 31
	s_lshl_b64 s[22:23], s[34:35], 19
	s_add_u32 s42, s8, s22
	s_addc_u32 s43, s9, s23
	s_and_b64 s[22:23], vcc, exec
	s_cselect_b32 s22, s43, s53
	s_cselect_b32 s23, s42, s52
	s_add_u32 s48, s48, 0x40080
	s_addc_u32 s49, s49, 0
	s_add_u32 s31, s52, 0x100
	s_addc_u32 s33, s53, 0
	s_mov_b32 s35, -2
	s_waitcnt lgkmcnt(0)
	ds_read_b128 v[48:51], v185
	ds_read_b128 v[52:55], v185 offset:1024
	ds_read_b128 v[56:59], v185 offset:2048
	ds_read_b128 v[60:63], v185 offset:3072
	s_add_u32 s47, s48, 0xfffc0080
	s_addc_u32 s50, s49, -1
	s_cmp_eq_u32 s35, 12
	s_cselect_b32 s55, s3, s50
	s_cselect_b32 s54, s21, s47
	s_cselect_b32 s53, s22, s33
	s_cselect_b32 s52, s23, s31
	v_lshl_add_u64 v[180:181], s[48:49], 0, v[164:165]
	s_add_i32 m0, s11, 0xc000
	ds_read_b128 v[144:147], v186
	ds_read_b128 v[148:151], v186 offset:1024
	ds_read_b128 v[152:155], v186 offset:2048
	ds_read_b128 v[156:159], v186 offset:3072
	ds_read_b128 v[172:175], v186 offset:4096
	ds_read_b128 v[176:179], v186 offset:5120
	ds_read_b128 v[188:191], v186 offset:6144
	ds_read_b128 v[192:195], v186 offset:7168
	global_load_lds_dwordx4 v[180:181], off
	v_lshl_add_u64 v[180:181], s[48:49], 0, v[166:167]
	s_add_i32 m0, s11, 0xe000
	s_nop 0
	global_load_lds_dwordx4 v[180:181], off
	s_cmpk_gt_u32 s5, 0xff
	s_cbranch_scc0 .Lhbar_out
	s_barrier
.Lhbar_out:
	s_waitcnt lgkmcnt(8)
	s_barrier
	s_waitcnt lgkmcnt(0)
	s_waitcnt lgkmcnt(0)
	v_mfma_f32_16x16x32_bf16 v[140:143], v[48:51], v[144:147], 0
	v_mfma_f32_16x16x32_bf16 v[136:139], v[56:59], v[144:147], 0
	v_mfma_f32_16x16x32_bf16 v[124:127], v[48:51], v[152:155], 0
	v_mfma_f32_16x16x32_bf16 v[120:123], v[56:59], v[152:155], 0
	v_mfma_f32_16x16x32_bf16 v[108:111], v[48:51], v[172:175], 0
	v_mfma_f32_16x16x32_bf16 v[104:107], v[56:59], v[172:175], 0
	v_mfma_f32_16x16x32_bf16 v[92:95], v[48:51], v[188:191], 0
	v_mfma_f32_16x16x32_bf16 v[88:91], v[56:59], v[188:191], 0
	v_mfma_f32_16x16x32_bf16 v[140:143], v[52:55], v[148:151], v[140:143]
	v_mfma_f32_16x16x32_bf16 v[136:139], v[60:63], v[148:151], v[136:139]
	v_mfma_f32_16x16x32_bf16 v[124:127], v[52:55], v[156:159], v[124:127]
	v_mfma_f32_16x16x32_bf16 v[120:123], v[60:63], v[156:159], v[120:123]
	v_mfma_f32_16x16x32_bf16 v[108:111], v[52:55], v[176:179], v[108:111]
	v_mfma_f32_16x16x32_bf16 v[104:107], v[60:63], v[176:179], v[104:107]
	v_mfma_f32_16x16x32_bf16 v[92:95], v[52:55], v[192:195], v[92:95]
	v_mfma_f32_16x16x32_bf16 v[88:91], v[60:63], v[192:195], v[88:91]
	s_barrier
	s_add_i32 s47, s19, s10
	v_lshl_add_u64 v[180:181], s[52:53], 0, v[160:161]
	s_mov_b32 m0, s47
	ds_read_b128 v[196:199], v187
	ds_read_b128 v[200:203], v187 offset:1024
	ds_read_b128 v[204:207], v187 offset:2048
	ds_read_b128 v[208:211], v187 offset:3072
	global_load_lds_dwordx4 v[180:181], off
	v_lshl_add_u64 v[212:213], s[52:53], 0, v[162:163]
	s_add_i32 m0, s47, 0x2000
	s_nop 0
	global_load_lds_dwordx4 v[212:213], off
	s_barrier
	s_waitcnt lgkmcnt(0)
	s_waitcnt lgkmcnt(0)
	v_mfma_f32_16x16x32_bf16 v[132:135], v[196:199], v[144:147], 0
	v_mfma_f32_16x16x32_bf16 v[128:131], v[204:207], v[144:147], 0
	v_mfma_f32_16x16x32_bf16 v[116:119], v[196:199], v[152:155], 0
	v_mfma_f32_16x16x32_bf16 v[112:115], v[204:207], v[152:155], 0
	v_mfma_f32_16x16x32_bf16 v[100:103], v[196:199], v[172:175], 0
	v_mfma_f32_16x16x32_bf16 v[96:99], v[204:207], v[172:175], 0
	v_mfma_f32_16x16x32_bf16 v[84:87], v[196:199], v[188:191], 0
	v_mfma_f32_16x16x32_bf16 v[80:83], v[204:207], v[188:191], 0
	v_mfma_f32_16x16x32_bf16 v[132:135], v[200:203], v[148:151], v[132:135]
	v_mfma_f32_16x16x32_bf16 v[128:131], v[208:211], v[148:151], v[128:131]
	v_mfma_f32_16x16x32_bf16 v[116:119], v[200:203], v[156:159], v[116:119]
	v_mfma_f32_16x16x32_bf16 v[112:115], v[208:211], v[156:159], v[112:115]
	v_mfma_f32_16x16x32_bf16 v[100:103], v[200:203], v[176:179], v[100:103]
	v_mfma_f32_16x16x32_bf16 v[96:99], v[208:211], v[176:179], v[96:99]
	v_mfma_f32_16x16x32_bf16 v[84:87], v[200:203], v[192:195], v[84:87]
	v_mfma_f32_16x16x32_bf16 v[80:83], v[208:211], v[192:195], v[80:83]
	s_mov_b32 m0, s11
	v_lshl_add_u64 v[214:215], s[54:55], 0, v[160:161]
	s_barrier
	ds_read_b128 v[144:147], v186 offset:16384
	ds_read_b128 v[148:151], v186 offset:17408
	ds_read_b128 v[152:155], v186 offset:18432
	ds_read_b128 v[156:159], v186 offset:19456
	ds_read_b128 v[172:175], v186 offset:20480
	ds_read_b128 v[176:179], v186 offset:21504
	ds_read_b128 v[188:191], v186 offset:22528
	ds_read_b128 v[192:195], v186 offset:23552
	global_load_lds_dwordx4 v[214:215], off
	v_lshl_add_u64 v[216:217], s[54:55], 0, v[162:163]
	s_mov_b32 m0, s12
	s_nop 0
	global_load_lds_dwordx4 v[216:217], off
	s_barrier
	s_waitcnt lgkmcnt(0)
	s_waitcnt lgkmcnt(0)
	v_mfma_f32_16x16x32_bf16 v[76:79], v[48:51], v[144:147], 0
	v_mfma_f32_16x16x32_bf16 v[72:75], v[56:59], v[144:147], 0
	v_mfma_f32_16x16x32_bf16 v[44:47], v[48:51], v[152:155], 0
	v_mfma_f32_16x16x32_bf16 v[40:43], v[56:59], v[152:155], 0
	v_mfma_f32_16x16x32_bf16 v[28:31], v[48:51], v[172:175], 0
	v_mfma_f32_16x16x32_bf16 v[24:27], v[56:59], v[172:175], 0
	v_mfma_f32_16x16x32_bf16 v[12:15], v[48:51], v[188:191], 0
	v_mfma_f32_16x16x32_bf16 v[8:11], v[56:59], v[188:191], 0
	v_mfma_f32_16x16x32_bf16 v[76:79], v[52:55], v[148:151], v[76:79]
	v_mfma_f32_16x16x32_bf16 v[72:75], v[60:63], v[148:151], v[72:75]
	v_mfma_f32_16x16x32_bf16 v[44:47], v[52:55], v[156:159], v[44:47]
	v_mfma_f32_16x16x32_bf16 v[40:43], v[60:63], v[156:159], v[40:43]
	v_mfma_f32_16x16x32_bf16 v[28:31], v[52:55], v[176:179], v[28:31]
	v_mfma_f32_16x16x32_bf16 v[24:27], v[60:63], v[176:179], v[24:27]
	v_mfma_f32_16x16x32_bf16 v[12:15], v[52:55], v[192:195], v[12:15]
	v_mfma_f32_16x16x32_bf16 v[8:11], v[60:63], v[192:195], v[8:11]
	s_barrier
	s_add_u32 s50, s52, 0x40000
	s_addc_u32 s51, s53, 0
	s_add_i32 s47, s20, s10
	v_lshl_add_u64 v[48:49], s[50:51], 0, v[160:161]
	s_mov_b32 m0, s47
	s_nop 0
	global_load_lds_dwordx4 v[48:49], off
	v_lshl_add_u64 v[48:49], s[50:51], 0, v[162:163]
	s_add_i32 m0, s47, 0x2000
	s_nop 0
	global_load_lds_dwordx4 v[48:49], off
	s_waitcnt vmcnt(6)
	s_barrier
	v_mfma_f32_16x16x32_bf16 v[36:39], v[196:199], v[152:155], 0
	v_mfma_f32_16x16x32_bf16 v[32:35], v[204:207], v[152:155], 0
	v_mfma_f32_16x16x32_bf16 v[20:23], v[196:199], v[172:175], 0
	v_mfma_f32_16x16x32_bf16 v[16:19], v[204:207], v[172:175], 0
	v_mfma_f32_16x16x32_bf16 v[4:7], v[196:199], v[188:191], 0
	v_mfma_f32_16x16x32_bf16 v[0:3], v[204:207], v[188:191], 0
	v_mfma_f32_16x16x32_bf16 v[48:51], v[196:199], v[144:147], 0
	v_mfma_f32_16x16x32_bf16 v[52:55], v[204:207], v[144:147], 0
	v_mfma_f32_16x16x32_bf16 v[36:39], v[200:203], v[156:159], v[36:39]
	v_mfma_f32_16x16x32_bf16 v[32:35], v[208:211], v[156:159], v[32:35]
	v_mfma_f32_16x16x32_bf16 v[20:23], v[200:203], v[176:179], v[20:23]
	v_mfma_f32_16x16x32_bf16 v[16:19], v[208:211], v[176:179], v[16:19]
	v_mfma_f32_16x16x32_bf16 v[4:7], v[200:203], v[192:195], v[4:7]
	v_mfma_f32_16x16x32_bf16 v[0:3], v[208:211], v[192:195], v[0:3]
	v_mfma_f32_16x16x32_bf16 v[48:51], v[200:203], v[148:151], v[48:51]
	v_mfma_f32_16x16x32_bf16 v[52:55], v[208:211], v[148:151], v[52:55]
	s_add_i32 s47, 0, 0x18000
	v_add_u32_e32 v68, s47, v183
	s_barrier
	ds_read_b128 v[56:59], v68
	ds_read_b128 v[60:63], v68 offset:1024
	ds_read_b128 v[64:67], v68 offset:2048
	ds_read_b128 v[68:71], v68 offset:3072
	s_add_u32 s50, s54, 0x40000
	s_addc_u32 s51, s55, 0
	s_mov_b32 m0, s13
	v_lshl_add_u64 v[196:197], s[50:51], 0, v[160:161]
	ds_read_b128 v[144:147], v186 offset:32768
	ds_read_b128 v[148:151], v186 offset:33792
	ds_read_b128 v[152:155], v186 offset:34816
	ds_read_b128 v[156:159], v186 offset:35840
	ds_read_b128 v[172:175], v186 offset:36864
	ds_read_b128 v[176:179], v186 offset:37888
	ds_read_b128 v[188:191], v186 offset:38912
	ds_read_b128 v[192:195], v186 offset:39936
	global_load_lds_dwordx4 v[196:197], off
	v_lshl_add_u64 v[196:197], s[50:51], 0, v[162:163]
	s_mov_b32 m0, s14
	s_nop 0
	global_load_lds_dwordx4 v[196:197], off
	s_waitcnt lgkmcnt(8)
	s_barrier
	s_waitcnt lgkmcnt(0)
	s_waitcnt lgkmcnt(0)
	v_mfma_f32_16x16x32_bf16 v[140:143], v[56:59], v[144:147], v[140:143]
	v_mfma_f32_16x16x32_bf16 v[136:139], v[64:67], v[144:147], v[136:139]
	v_mfma_f32_16x16x32_bf16 v[124:127], v[56:59], v[152:155], v[124:127]
	v_mfma_f32_16x16x32_bf16 v[120:123], v[64:67], v[152:155], v[120:123]
	v_mfma_f32_16x16x32_bf16 v[108:111], v[56:59], v[172:175], v[108:111]
	v_mfma_f32_16x16x32_bf16 v[104:107], v[64:67], v[172:175], v[104:107]
	v_mfma_f32_16x16x32_bf16 v[92:95], v[56:59], v[188:191], v[92:95]
	v_mfma_f32_16x16x32_bf16 v[88:91], v[64:67], v[188:191], v[88:91]
	v_mfma_f32_16x16x32_bf16 v[140:143], v[60:63], v[148:151], v[140:143]
	v_mfma_f32_16x16x32_bf16 v[136:139], v[68:71], v[148:151], v[136:139]
	v_mfma_f32_16x16x32_bf16 v[124:127], v[60:63], v[156:159], v[124:127]
	v_mfma_f32_16x16x32_bf16 v[120:123], v[68:71], v[156:159], v[120:123]
	v_mfma_f32_16x16x32_bf16 v[108:111], v[60:63], v[176:179], v[108:111]
	v_mfma_f32_16x16x32_bf16 v[104:107], v[68:71], v[176:179], v[104:107]
	v_mfma_f32_16x16x32_bf16 v[92:95], v[60:63], v[192:195], v[92:95]
	v_mfma_f32_16x16x32_bf16 v[88:91], v[68:71], v[192:195], v[88:91]
	s_barrier
	s_add_i32 s54, 0, 0x1c000
	s_add_i32 s47, s47, s10
	v_add_u32_e32 v208, s54, v183
	v_lshl_add_u64 v[180:181], v[180:181], 0, s[28:29]
	s_mov_b32 m0, s47
	ds_read_b128 v[196:199], v208
	ds_read_b128 v[200:203], v208 offset:1024
	ds_read_b128 v[204:207], v208 offset:2048
	ds_read_b128 v[208:211], v208 offset:3072
	global_load_lds_dwordx4 v[180:181], off
	v_lshl_add_u64 v[180:181], v[212:213], 0, s[28:29]
	s_add_i32 m0, s47, 0x2000
	s_nop 0
	global_load_lds_dwordx4 v[180:181], off
	s_barrier
	s_waitcnt lgkmcnt(0)
	s_waitcnt lgkmcnt(0)
	v_mfma_f32_16x16x32_bf16 v[132:135], v[196:199], v[144:147], v[132:135]
	v_mfma_f32_16x16x32_bf16 v[128:131], v[204:207], v[144:147], v[128:131]
	v_mfma_f32_16x16x32_bf16 v[116:119], v[196:199], v[152:155], v[116:119]
	v_mfma_f32_16x16x32_bf16 v[112:115], v[204:207], v[152:155], v[112:115]
	v_mfma_f32_16x16x32_bf16 v[100:103], v[196:199], v[172:175], v[100:103]
	v_mfma_f32_16x16x32_bf16 v[96:99], v[204:207], v[172:175], v[96:99]
	v_mfma_f32_16x16x32_bf16 v[84:87], v[196:199], v[188:191], v[84:87]
	v_mfma_f32_16x16x32_bf16 v[80:83], v[204:207], v[188:191], v[80:83]
	v_mfma_f32_16x16x32_bf16 v[132:135], v[200:203], v[148:151], v[132:135]
	v_mfma_f32_16x16x32_bf16 v[128:131], v[208:211], v[148:151], v[128:131]
	v_mfma_f32_16x16x32_bf16 v[116:119], v[200:203], v[156:159], v[116:119]
	v_mfma_f32_16x16x32_bf16 v[112:115], v[208:211], v[156:159], v[112:115]
	v_mfma_f32_16x16x32_bf16 v[100:103], v[200:203], v[176:179], v[100:103]
	v_mfma_f32_16x16x32_bf16 v[96:99], v[208:211], v[176:179], v[96:99]
	v_mfma_f32_16x16x32_bf16 v[84:87], v[200:203], v[192:195], v[84:87]
	v_mfma_f32_16x16x32_bf16 v[80:83], v[208:211], v[192:195], v[80:83]
	s_mov_b32 m0, s16
	v_lshl_add_u64 v[180:181], v[214:215], 0, s[28:29]
	s_barrier
	ds_read_b128 v[144:147], v186 offset:49152
	ds_read_b128 v[148:151], v186 offset:50176
	ds_read_b128 v[152:155], v186 offset:51200
	ds_read_b128 v[156:159], v186 offset:52224
	ds_read_b128 v[172:175], v186 offset:53248
	ds_read_b128 v[176:179], v186 offset:54272
	ds_read_b128 v[188:191], v186 offset:55296
	ds_read_b128 v[192:195], v186 offset:56320
	global_load_lds_dwordx4 v[180:181], off
	v_lshl_add_u64 v[180:181], v[216:217], 0, s[28:29]
	s_mov_b32 m0, s17
	s_nop 0
	global_load_lds_dwordx4 v[180:181], off
	s_barrier
	s_waitcnt lgkmcnt(0)
	s_waitcnt lgkmcnt(0)
	v_mfma_f32_16x16x32_bf16 v[76:79], v[56:59], v[144:147], v[76:79]
	v_mfma_f32_16x16x32_bf16 v[72:75], v[64:67], v[144:147], v[72:75]
	v_mfma_f32_16x16x32_bf16 v[44:47], v[56:59], v[152:155], v[44:47]
	v_mfma_f32_16x16x32_bf16 v[40:43], v[64:67], v[152:155], v[40:43]
	v_mfma_f32_16x16x32_bf16 v[28:31], v[56:59], v[172:175], v[28:31]
	v_mfma_f32_16x16x32_bf16 v[24:27], v[64:67], v[172:175], v[24:27]
	v_mfma_f32_16x16x32_bf16 v[12:15], v[56:59], v[188:191], v[12:15]
	v_mfma_f32_16x16x32_bf16 v[8:11], v[64:67], v[188:191], v[8:11]
	v_mfma_f32_16x16x32_bf16 v[76:79], v[60:63], v[148:151], v[76:79]
	v_mfma_f32_16x16x32_bf16 v[72:75], v[68:71], v[148:151], v[72:75]
	v_mfma_f32_16x16x32_bf16 v[44:47], v[60:63], v[156:159], v[44:47]
	v_mfma_f32_16x16x32_bf16 v[40:43], v[68:71], v[156:159], v[40:43]
	v_mfma_f32_16x16x32_bf16 v[28:31], v[60:63], v[176:179], v[28:31]
	v_mfma_f32_16x16x32_bf16 v[24:27], v[68:71], v[176:179], v[24:27]
	v_mfma_f32_16x16x32_bf16 v[12:15], v[60:63], v[192:195], v[12:15]
	v_mfma_f32_16x16x32_bf16 v[8:11], v[68:71], v[192:195], v[8:11]
	s_barrier
	s_add_u32 s50, s52, 0x40080
	s_addc_u32 s51, s53, 0
	s_add_i32 s47, s54, s10
	v_lshl_add_u64 v[56:57], s[50:51], 0, v[160:161]
	s_mov_b32 m0, s47
	s_nop 0
	global_load_lds_dwordx4 v[56:57], off
	v_lshl_add_u64 v[56:57], s[50:51], 0, v[162:163]
	s_add_i32 m0, s47, 0x2000
	s_nop 0
	global_load_lds_dwordx4 v[56:57], off
	s_waitcnt vmcnt(6)
	s_barrier
	v_mfma_f32_16x16x32_bf16 v[48:51], v[196:199], v[144:147], v[48:51]
	v_mfma_f32_16x16x32_bf16 v[68:71], v[200:203], v[148:151], v[48:51]
	v_mfma_f32_16x16x32_bf16 v[48:51], v[204:207], v[144:147], v[52:55]
	v_mfma_f32_16x16x32_bf16 v[36:39], v[196:199], v[152:155], v[36:39]
	v_mfma_f32_16x16x32_bf16 v[32:35], v[204:207], v[152:155], v[32:35]
	v_mfma_f32_16x16x32_bf16 v[20:23], v[196:199], v[172:175], v[20:23]
	v_mfma_f32_16x16x32_bf16 v[16:19], v[204:207], v[172:175], v[16:19]
	v_mfma_f32_16x16x32_bf16 v[4:7], v[196:199], v[188:191], v[4:7]
	v_mfma_f32_16x16x32_bf16 v[0:3], v[204:207], v[188:191], v[0:3]
	v_mfma_f32_16x16x32_bf16 v[64:67], v[208:211], v[148:151], v[48:51]
	v_mfma_f32_16x16x32_bf16 v[36:39], v[200:203], v[156:159], v[36:39]
	v_mfma_f32_16x16x32_bf16 v[32:35], v[208:211], v[156:159], v[32:35]
	v_mfma_f32_16x16x32_bf16 v[20:23], v[200:203], v[176:179], v[20:23]
	v_mfma_f32_16x16x32_bf16 v[16:19], v[208:211], v[176:179], v[16:19]
	v_mfma_f32_16x16x32_bf16 v[4:7], v[200:203], v[192:195], v[4:7]
	v_mfma_f32_16x16x32_bf16 v[0:3], v[208:211], v[192:195], v[0:3]
	s_add_i32 s35, s35, 2
	s_add_u32 s48, s48, 0x100
	s_addc_u32 s49, s49, 0
	s_add_u32 s31, s31, 0x100
	s_addc_u32 s33, s33, 0
	s_cmp_gt_u32 s35, 13
	s_barrier

.LBB0_635:
	s_waitcnt vmcnt(0)
	s_cmpk_gt_u32 s5, 0xff
	s_cbranch_scc1 .LBB0_637
.LBB0_637:
	s_barrier

.LBB0_698:
	v_readlane_b32 s20, v254, 1
	v_readlane_b32 s21, v254, 2
	v_readlane_b32 s22, v254, 3
	v_readlane_b32 s23, v254, 4
	v_readlane_b32 s24, v254, 5
	v_readlane_b32 s25, v254, 6
	v_readlane_b32 s26, v254, 7
	v_readlane_b32 s27, v254, 8
	s_mov_b64 s[20:21], s[24:25]
	s_add_u32 s96, s20, 0x2c00
	s_addc_u32 s97, s21, 0
	s_add_u32 s86, s20, 0x5800
	s_addc_u32 s87, s21, 0
	s_add_u32 s28, s2, 0x21c00000
	s_addc_u32 s29, s3, 0
	s_add_u32 s30, s2, 0x14000000
	v_lshrrev_b32_e32 v16, 1, v8
	s_addc_u32 s31, s3, 0
	v_and_b32_e32 v16, 24, v16
	s_add_u32 s34, s2, 0x12000000
	v_and_b32_e32 v15, 15, v8
	v_lshlrev_b32_e32 v17, 1, v16
	v_lshlrev_b32_e32 v18, 2, v8
	s_addc_u32 s35, s3, 0
	v_lshl_or_b32 v17, v15, 6, v17
	s_lshl_b32 s2, s10, 13
	v_and_b32_e32 v18, 32, v18
	v_bitop3_b32 v19, v17, s2, v18 bitop3:0xde
	s_lshl_b32 s2, s17, 5
	s_mov_b64 s[52:53], 0x80
	s_and_b32 s20, s2, 0x60
	s_add_i32 m0, s12, 0x18000
	v_lshl_add_u64 v[6:7], v[6:7], 0, s[52:53]
	s_lshl_b32 s2, s20, 7
	s_waitcnt vmcnt(4)
	s_barrier
	global_load_lds_dwordx4 v[6:7], off
	v_lshl_add_u64 v[4:5], v[4:5], 0, s[52:53]
	s_add_i32 m0, s12, 0x1a000
	s_add_i32 s17, s12, 0x8000
	s_add_i32 s18, s12, 0xa000
	v_bitop3_b32 v232, v17, s2, v18 bitop3:0xde
	global_load_lds_dwordx4 v[4:5], off
	v_lshl_add_u64 v[2:3], v[2:3], 0, s[52:53]
	s_mov_b32 m0, s17
	s_add_u32 s2, s0, 0x40080
	global_load_lds_dwordx4 v[2:3], off
	v_lshl_add_u64 v[0:1], v[0:1], 0, s[52:53]
	s_mov_b32 m0, s18
	s_addc_u32 s3, s1, 0
	global_load_lds_dwordx4 v[0:1], off
	s_add_i32 m0, s12, 0x1c000
	v_lshl_add_u64 v[0:1], s[2:3], 0, v[160:161]
	global_load_lds_dwordx4 v[0:1], off
	v_lshl_add_u64 v[0:1], s[2:3], 0, v[162:163]
	s_add_i32 m0, s12, 0x1e000
	v_cmp_eq_u32_e64 s[38:39], 15, v15
	global_load_lds_dwordx4 v[0:1], off
	s_nop 0
	v_cndmask_b32_e64 v0, -1, 3, s[38:39]
	v_cmp_ne_u32_e32 vcc, 14, v15
	v_cmp_eq_u32_e64 s[42:43], 0, v15
	v_and_b32_e32 v1, 1, v9
	v_cndmask_b32_e32 v233, 2, v0, vcc
	v_cmp_eq_u32_e32 vcc, 1, v15
	s_waitcnt vmcnt(6)
	v_or_b32_e32 v235, s20, v16
	s_add_i32 s20, 0, 0x10000
	v_cndmask_b32_e64 v0, -1, 1, vcc
	v_cndmask_b32_e64 v234, v0, 0, s[42:43]
	v_and_b32_e32 v0, 14, v8
	v_cmp_eq_u32_e64 s[74:75], 14, v0
	v_lshlrev_b32_e32 v0, 14, v9
	v_and_b32_e32 v0, 0xffff8000, v0
	v_lshl_add_u32 v0, v10, 11, v0
	v_lshl_or_b32 v0, v1, 6, v0
	v_lshl_add_u32 v166, v11, 1, v0
	v_lshlrev_b32_e32 v0, 14, v12
	v_and_b32_e32 v0, 0xffff8000, v0
	v_lshl_add_u32 v0, v13, 11, v0
	v_and_b32_e32 v1, 1, v12
	v_lshl_or_b32 v0, v1, 6, v0
	s_add_i32 s21, 0, 0x14000
	v_lshl_or_b32 v231, s10, 6, v15
	v_cmp_ne_u32_e64 s[36:37], 15, v15
	v_cmp_ne_u32_e64 s[40:41], 0, v15
	v_cmp_gt_u32_e64 s[70:71], 2, v15
	s_ashr_i32 s19, s4, 31
	v_mov_b32_e32 v167, v165
	v_lshl_add_u32 v168, v14, 1, v0
	v_mov_b32_e32 v169, v165
	v_mov_b64_e32 v[170:171], 0x1600
	v_mov_b64_e32 v[172:173], 0x15ff
	v_add_u32_e32 v236, s20, v232
	v_add_u32_e32 v237, 0, v19
	v_add_u32_e32 v238, s21, v232
	v_mov_b32_e32 v239, 0x358637bd
	s_mov_b32 s33, 0x800000
	s_movk_i32 s65, 0xb00
	s_mov_b32 s54, 0xbf38aa3b
	s_mov_b32 s56, 0x3e6d3388
	s_mov_b32 s58, 0x3f07dc22
	s_mov_b32 s64, 0xbf3a00e3
	s_mov_b32 s66, 0x3f35f0e3
	s_mov_b32 s68, 0xbe11a98e
	s_mov_b32 s72, 0x3e027906
	s_mov_b64 s[22:23], s[26:27]
	s_barrier
	s_cmpk_gt_u32 s5, 0xff
	s_cbranch_scc1 .Lepix_ffnin
	s_barrier
.Lepix_ffnin:
	s_branch .LBB0_700
	s_nop 0
	s_nop 0

.LBB0_702:
	s_ashr_i32 s63, s62, 31
	s_lshl_b64 s[22:23], s[62:63], 19
	s_add_u32 s26, s6, s22
	v_cmp_lt_i64_e32 vcc, s[24:25], v[170:171]
	s_addc_u32 s27, s7, s23
	s_and_b64 s[22:23], vcc, exec
	s_cselect_b32 s22, s27, s91
	s_cselect_b32 s23, s26, s90
	s_ashr_i32 s3, s2, 31
	s_lshl_b64 s[24:25], s[2:3], 19
	s_add_u32 s24, s8, s24
	s_addc_u32 s25, s9, s25
	s_and_b64 s[60:61], vcc, exec
	s_cselect_b32 s3, s25, s1
	s_cselect_b32 s51, s24, s0
	s_add_u32 vcc_lo, s90, 0x40080
	s_addc_u32 vcc_hi, s91, 0
	s_add_u32 s55, s0, 0x100
	s_addc_u32 s57, s1, 0
	s_mov_b32 s59, -2
	ds_read_b128 v[44:47], v236
	ds_read_b128 v[48:51], v236 offset:1024
	ds_read_b128 v[52:55], v236 offset:2048
	ds_read_b128 v[56:59], v236 offset:3072
	s_add_u32 s0, vcc_lo, 0xfffc0080
	s_addc_u32 s1, vcc_hi, -1
	s_cmp_eq_u32 s59, 12
	s_cselect_b32 s91, s22, s1
	s_cselect_b32 s90, s23, s0
	s_cselect_b32 s1, s3, s57
	s_cselect_b32 s0, s51, s55
	v_lshl_add_u64 v[190:191], vcc, 0, v[166:167]
	s_add_i32 m0, s12, 0xc000
	ds_read_b128 v[68:71], v237
	ds_read_b128 v[72:75], v237 offset:1024
	ds_read_b128 v[76:79], v237 offset:2048
	ds_read_b128 v[80:83], v237 offset:3072
	ds_read_b128 v[174:177], v237 offset:4096
	ds_read_b128 v[178:181], v237 offset:5120
	ds_read_b128 v[182:185], v237 offset:6144
	ds_read_b128 v[186:189], v237 offset:7168
	global_load_lds_dwordx4 v[190:191], off
	v_lshl_add_u64 v[190:191], vcc, 0, v[168:169]
	s_add_i32 m0, s12, 0xe000
	s_nop 0
	global_load_lds_dwordx4 v[190:191], off
	s_cmpk_gt_u32 s5, 0xff
	s_cbranch_scc0 .Lhbar_ffnin
	s_barrier
.Lhbar_ffnin:
	s_waitcnt lgkmcnt(8)
	s_barrier
	s_waitcnt lgkmcnt(0)
	s_waitcnt lgkmcnt(0)
	v_mfma_f32_16x16x32_bf16 v[156:159], v[44:47], v[68:71], 0
	v_mfma_f32_16x16x32_bf16 v[132:135], v[52:55], v[68:71], 0
	v_mfma_f32_16x16x32_bf16 v[152:155], v[44:47], v[76:79], 0
	v_mfma_f32_16x16x32_bf16 v[128:131], v[52:55], v[76:79], 0
	v_mfma_f32_16x16x32_bf16 v[140:143], v[44:47], v[174:177], 0
	v_mfma_f32_16x16x32_bf16 v[104:107], v[52:55], v[174:177], 0
	v_mfma_f32_16x16x32_bf16 v[144:147], v[44:47], v[182:185], 0
	v_mfma_f32_16x16x32_bf16 v[108:111], v[52:55], v[182:185], 0
	v_mfma_f32_16x16x32_bf16 v[156:159], v[48:51], v[72:75], v[156:159]
	v_mfma_f32_16x16x32_bf16 v[132:135], v[56:59], v[72:75], v[132:135]
	v_mfma_f32_16x16x32_bf16 v[152:155], v[48:51], v[80:83], v[152:155]
	v_mfma_f32_16x16x32_bf16 v[128:131], v[56:59], v[80:83], v[128:131]
	v_mfma_f32_16x16x32_bf16 v[140:143], v[48:51], v[178:181], v[140:143]
	v_mfma_f32_16x16x32_bf16 v[104:107], v[56:59], v[178:181], v[104:107]
	v_mfma_f32_16x16x32_bf16 v[144:147], v[48:51], v[186:189], v[144:147]
	v_mfma_f32_16x16x32_bf16 v[108:111], v[56:59], v[186:189], v[108:111]
	s_barrier
	s_add_i32 s60, s20, s11
	v_lshl_add_u64 v[214:215], s[0:1], 0, v[160:161]
	s_mov_b32 m0, s60
	ds_read_b128 v[190:193], v238
	ds_read_b128 v[194:197], v238 offset:1024
	ds_read_b128 v[198:201], v238 offset:2048
	ds_read_b128 v[202:205], v238 offset:3072
	global_load_lds_dwordx4 v[214:215], off
	v_lshl_add_u64 v[216:217], s[0:1], 0, v[162:163]
	s_add_i32 m0, s60, 0x2000
	s_nop 0
	global_load_lds_dwordx4 v[216:217], off
	s_barrier
	s_waitcnt lgkmcnt(0)
	s_waitcnt lgkmcnt(0)
	v_mfma_f32_16x16x32_bf16 v[148:151], v[190:193], v[68:71], 0
	v_mfma_f32_16x16x32_bf16 v[68:71], v[198:201], v[68:71], 0
	v_mfma_f32_16x16x32_bf16 v[148:151], v[194:197], v[72:75], v[148:151]
	v_mfma_f32_16x16x32_bf16 v[68:71], v[202:205], v[72:75], v[68:71]
	v_mfma_f32_16x16x32_bf16 v[72:75], v[190:193], v[76:79], 0
	v_mfma_f32_16x16x32_bf16 v[76:79], v[198:201], v[76:79], 0
	v_mfma_f32_16x16x32_bf16 v[100:103], v[198:201], v[174:177], 0
	v_mfma_f32_16x16x32_bf16 v[112:115], v[190:193], v[182:185], 0
	v_mfma_f32_16x16x32_bf16 v[96:99], v[198:201], v[182:185], 0
	v_mfma_f32_16x16x32_bf16 v[72:75], v[194:197], v[80:83], v[72:75]
	v_mfma_f32_16x16x32_bf16 v[76:79], v[202:205], v[80:83], v[76:79]
	v_mfma_f32_16x16x32_bf16 v[80:83], v[190:193], v[174:177], 0
	v_mfma_f32_16x16x32_bf16 v[100:103], v[202:205], v[178:181], v[100:103]
	v_mfma_f32_16x16x32_bf16 v[136:139], v[194:197], v[186:189], v[112:115]
	v_mfma_f32_16x16x32_bf16 v[96:99], v[202:205], v[186:189], v[96:99]
	v_mfma_f32_16x16x32_bf16 v[80:83], v[194:197], v[178:181], v[80:83]
	s_mov_b32 m0, s12
	v_lshl_add_u64 v[218:219], s[90:91], 0, v[160:161]
	s_barrier
	ds_read_b128 v[112:115], v237 offset:16384
	ds_read_b128 v[116:119], v237 offset:17408
	ds_read_b128 v[120:123], v237 offset:18432
	ds_read_b128 v[124:127], v237 offset:19456
	ds_read_b128 v[174:177], v237 offset:20480
	ds_read_b128 v[178:181], v237 offset:21504
	ds_read_b128 v[182:185], v237 offset:22528
	ds_read_b128 v[186:189], v237 offset:23552
	global_load_lds_dwordx4 v[218:219], off
	v_lshl_add_u64 v[220:221], s[90:91], 0, v[162:163]
	s_mov_b32 m0, s13
	s_nop 0
	global_load_lds_dwordx4 v[220:221], off
	s_barrier
	s_waitcnt lgkmcnt(0)
	s_waitcnt lgkmcnt(0)
	v_mfma_f32_16x16x32_bf16 v[92:95], v[44:47], v[112:115], 0
	v_mfma_f32_16x16x32_bf16 v[40:43], v[52:55], v[112:115], 0
	v_mfma_f32_16x16x32_bf16 v[88:91], v[44:47], v[120:123], 0
	v_mfma_f32_16x16x32_bf16 v[36:39], v[52:55], v[120:123], 0
	v_mfma_f32_16x16x32_bf16 v[60:63], v[44:47], v[174:177], 0
	v_mfma_f32_16x16x32_bf16 v[8:11], v[52:55], v[174:177], 0
	v_mfma_f32_16x16x32_bf16 v[16:19], v[52:55], v[182:185], 0
	v_mfma_f32_16x16x32_bf16 v[92:95], v[48:51], v[116:119], v[92:95]
	v_mfma_f32_16x16x32_bf16 v[40:43], v[56:59], v[116:119], v[40:43]
	v_mfma_f32_16x16x32_bf16 v[88:91], v[48:51], v[124:127], v[88:91]
	v_mfma_f32_16x16x32_bf16 v[36:39], v[56:59], v[124:127], v[36:39]
	v_mfma_f32_16x16x32_bf16 v[60:63], v[48:51], v[178:181], v[60:63]
	v_mfma_f32_16x16x32_bf16 v[8:11], v[56:59], v[178:181], v[8:11]
	v_mfma_f32_16x16x32_bf16 v[44:47], v[44:47], v[182:185], 0
	v_mfma_f32_16x16x32_bf16 v[16:19], v[56:59], v[186:189], v[16:19]
	v_mfma_f32_16x16x32_bf16 v[44:47], v[48:51], v[186:189], v[44:47]
	s_barrier
	s_add_u32 s60, s0, 0x40000
	s_addc_u32 s61, s1, 0
	s_add_i32 s63, s21, s11
	v_lshl_add_u64 v[48:49], s[60:61], 0, v[160:161]
	s_mov_b32 m0, s63
	s_nop 0
	global_load_lds_dwordx4 v[48:49], off
	v_lshl_add_u64 v[48:49], s[60:61], 0, v[162:163]
	s_add_i32 m0, s63, 0x2000
	s_nop 0
	global_load_lds_dwordx4 v[48:49], off
	s_waitcnt vmcnt(6)
	s_barrier
	v_mfma_f32_16x16x32_bf16 v[28:31], v[198:201], v[112:115], 0
	v_mfma_f32_16x16x32_bf16 v[24:27], v[190:193], v[120:123], 0
	v_mfma_f32_16x16x32_bf16 v[12:15], v[198:201], v[120:123], 0
	v_mfma_f32_16x16x32_bf16 v[20:23], v[190:193], v[174:177], 0
	v_mfma_f32_16x16x32_bf16 v[4:7], v[198:201], v[174:177], 0
	v_mfma_f32_16x16x32_bf16 v[32:35], v[190:193], v[182:185], 0
	v_mfma_f32_16x16x32_bf16 v[0:3], v[198:201], v[182:185], 0
	v_mfma_f32_16x16x32_bf16 v[48:51], v[190:193], v[112:115], 0
	v_mfma_f32_16x16x32_bf16 v[28:31], v[202:205], v[116:119], v[28:31]
	v_mfma_f32_16x16x32_bf16 v[24:27], v[194:197], v[124:127], v[24:27]
	v_mfma_f32_16x16x32_bf16 v[12:15], v[202:205], v[124:127], v[12:15]
	v_mfma_f32_16x16x32_bf16 v[20:23], v[194:197], v[178:181], v[20:23]
	v_mfma_f32_16x16x32_bf16 v[4:7], v[202:205], v[178:181], v[4:7]
	v_mfma_f32_16x16x32_bf16 v[32:35], v[194:197], v[186:189], v[32:35]
	v_mfma_f32_16x16x32_bf16 v[0:3], v[202:205], v[186:189], v[0:3]
	v_mfma_f32_16x16x32_bf16 v[48:51], v[194:197], v[116:119], v[48:51]
	s_add_i32 s63, 0, 0x18000
	v_add_u32_e32 v64, s63, v232
	s_barrier
	ds_read_b128 v[52:55], v64
	ds_read_b128 v[56:59], v64 offset:1024
	ds_read_b128 v[84:87], v64 offset:2048
	ds_read_b128 v[174:177], v64 offset:3072
	s_add_u32 s60, s90, 0x40000
	s_addc_u32 s61, s91, 0
	s_mov_b32 m0, s14
	v_lshl_add_u64 v[120:121], s[60:61], 0, v[160:161]
	ds_read_b128 v[64:67], v237 offset:32768
	ds_read_b128 v[112:115], v237 offset:33792
	ds_read_b128 v[116:119], v237 offset:34816
	ds_read_b128 v[178:181], v237 offset:35840
	ds_read_b128 v[182:185], v237 offset:36864
	ds_read_b128 v[186:189], v237 offset:37888
	ds_read_b128 v[190:193], v237 offset:38912
	ds_read_b128 v[194:197], v237 offset:39936
	global_load_lds_dwordx4 v[120:121], off
	v_lshl_add_u64 v[120:121], s[60:61], 0, v[162:163]
	s_mov_b32 m0, s15
	s_nop 0
	global_load_lds_dwordx4 v[120:121], off
	s_waitcnt lgkmcnt(8)
	s_barrier
	s_waitcnt lgkmcnt(0)
	s_waitcnt lgkmcnt(0)
	v_mfma_f32_16x16x32_bf16 v[120:123], v[52:55], v[64:67], v[156:159]
	v_mfma_f32_16x16x32_bf16 v[156:159], v[56:59], v[112:115], v[120:123]
	v_mfma_f32_16x16x32_bf16 v[120:123], v[84:87], v[64:67], v[132:135]
	v_mfma_f32_16x16x32_bf16 v[132:135], v[174:177], v[112:115], v[120:123]
	v_mfma_f32_16x16x32_bf16 v[120:123], v[52:55], v[116:119], v[152:155]
	v_mfma_f32_16x16x32_bf16 v[152:155], v[56:59], v[178:181], v[120:123]
	v_mfma_f32_16x16x32_bf16 v[120:123], v[84:87], v[116:119], v[128:131]
	v_mfma_f32_16x16x32_bf16 v[128:131], v[174:177], v[178:181], v[120:123]
	v_mfma_f32_16x16x32_bf16 v[120:123], v[52:55], v[182:185], v[140:143]
	v_mfma_f32_16x16x32_bf16 v[140:143], v[56:59], v[186:189], v[120:123]
	v_mfma_f32_16x16x32_bf16 v[104:107], v[84:87], v[182:185], v[104:107]
	v_mfma_f32_16x16x32_bf16 v[120:123], v[52:55], v[190:193], v[144:147]
	v_mfma_f32_16x16x32_bf16 v[108:111], v[84:87], v[190:193], v[108:111]
	v_mfma_f32_16x16x32_bf16 v[104:107], v[174:177], v[186:189], v[104:107]
	v_mfma_f32_16x16x32_bf16 v[144:147], v[56:59], v[194:197], v[120:123]
	v_mfma_f32_16x16x32_bf16 v[108:111], v[174:177], v[194:197], v[108:111]
	s_barrier
	s_add_i32 s60, 0, 0x1c000
	s_nop 0
	v_add_u32_e32 v120, s60, v232
	s_add_i32 s61, s63, s11
	ds_read_b128 v[198:201], v120
	ds_read_b128 v[202:205], v120 offset:1024
	ds_read_b128 v[206:209], v120 offset:2048
	ds_read_b128 v[210:213], v120 offset:3072
	v_lshl_add_u64 v[120:121], v[214:215], 0, s[52:53]
	s_mov_b32 m0, s61
	s_nop 0
	global_load_lds_dwordx4 v[120:121], off
	v_lshl_add_u64 v[120:121], v[216:217], 0, s[52:53]
	s_add_i32 m0, s61, 0x2000
	s_nop 0
	global_load_lds_dwordx4 v[120:121], off
	s_barrier
	s_waitcnt lgkmcnt(0)
	s_waitcnt lgkmcnt(0)
	v_mfma_f32_16x16x32_bf16 v[120:123], v[198:201], v[64:67], v[148:151]
	v_mfma_f32_16x16x32_bf16 v[64:67], v[206:209], v[64:67], v[68:71]
	v_mfma_f32_16x16x32_bf16 v[124:127], v[210:213], v[112:115], v[64:67]
	v_mfma_f32_16x16x32_bf16 v[64:67], v[198:201], v[116:119], v[72:75]
	v_mfma_f32_16x16x32_bf16 v[148:151], v[202:205], v[112:115], v[120:123]
	v_mfma_f32_16x16x32_bf16 v[120:123], v[202:205], v[178:181], v[64:67]
	v_mfma_f32_16x16x32_bf16 v[64:67], v[206:209], v[116:119], v[76:79]
	v_mfma_f32_16x16x32_bf16 v[112:115], v[210:213], v[178:181], v[64:67]
	v_mfma_f32_16x16x32_bf16 v[64:67], v[198:201], v[182:185], v[80:83]
	v_mfma_f32_16x16x32_bf16 v[116:119], v[202:205], v[186:189], v[64:67]
	v_mfma_f32_16x16x32_bf16 v[64:67], v[206:209], v[182:185], v[100:103]
	v_mfma_f32_16x16x32_bf16 v[100:103], v[210:213], v[186:189], v[64:67]
	v_mfma_f32_16x16x32_bf16 v[64:67], v[198:201], v[190:193], v[136:139]
	v_mfma_f32_16x16x32_bf16 v[136:139], v[202:205], v[194:197], v[64:67]
	v_mfma_f32_16x16x32_bf16 v[64:67], v[206:209], v[190:193], v[96:99]
	v_mfma_f32_16x16x32_bf16 v[96:99], v[210:213], v[194:197], v[64:67]
	s_mov_b32 m0, s17
	s_nop 4
	v_lshl_add_u64 v[64:65], v[218:219], 0, s[52:53]
	s_barrier
	ds_read_b128 v[68:71], v237 offset:49152
	ds_read_b128 v[72:75], v237 offset:50176
	ds_read_b128 v[76:79], v237 offset:51200
	ds_read_b128 v[80:83], v237 offset:52224
	ds_read_b128 v[178:181], v237 offset:53248
	ds_read_b128 v[182:185], v237 offset:54272
	ds_read_b128 v[186:189], v237 offset:55296
	ds_read_b128 v[190:193], v237 offset:56320
	global_load_lds_dwordx4 v[64:65], off
	v_lshl_add_u64 v[64:65], v[220:221], 0, s[52:53]
	s_mov_b32 m0, s18
	s_nop 0
	global_load_lds_dwordx4 v[64:65], off
	s_barrier
	s_waitcnt lgkmcnt(0)
	s_waitcnt lgkmcnt(0)
	v_mfma_f32_16x16x32_bf16 v[64:67], v[52:55], v[68:71], v[92:95]
	v_mfma_f32_16x16x32_bf16 v[92:95], v[56:59], v[72:75], v[64:67]
	v_mfma_f32_16x16x32_bf16 v[40:43], v[84:87], v[68:71], v[40:43]
	v_mfma_f32_16x16x32_bf16 v[64:67], v[52:55], v[76:79], v[88:91]
	v_mfma_f32_16x16x32_bf16 v[36:39], v[84:87], v[76:79], v[36:39]
	v_mfma_f32_16x16x32_bf16 v[60:63], v[52:55], v[178:181], v[60:63]
	v_mfma_f32_16x16x32_bf16 v[8:11], v[84:87], v[178:181], v[8:11]
	v_mfma_f32_16x16x32_bf16 v[44:47], v[52:55], v[186:189], v[44:47]
	v_mfma_f32_16x16x32_bf16 v[16:19], v[84:87], v[186:189], v[16:19]
	v_mfma_f32_16x16x32_bf16 v[40:43], v[174:177], v[72:75], v[40:43]
	v_mfma_f32_16x16x32_bf16 v[88:91], v[56:59], v[80:83], v[64:67]
	v_mfma_f32_16x16x32_bf16 v[36:39], v[174:177], v[80:83], v[36:39]
	v_mfma_f32_16x16x32_bf16 v[60:63], v[56:59], v[182:185], v[60:63]
	v_mfma_f32_16x16x32_bf16 v[8:11], v[174:177], v[182:185], v[8:11]
	v_mfma_f32_16x16x32_bf16 v[64:67], v[56:59], v[190:193], v[44:47]
	v_mfma_f32_16x16x32_bf16 v[16:19], v[174:177], v[190:193], v[16:19]
	s_barrier
	s_add_u32 s0, s0, 0x40080
	s_addc_u32 s1, s1, 0
	s_add_i32 s60, s60, s11
	v_lshl_add_u64 v[44:45], s[0:1], 0, v[160:161]
	s_mov_b32 m0, s60
	s_nop 0
	global_load_lds_dwordx4 v[44:45], off
	v_lshl_add_u64 v[44:45], s[0:1], 0, v[162:163]
	s_add_i32 m0, s60, 0x2000
	s_nop 0
	global_load_lds_dwordx4 v[44:45], off
	s_waitcnt vmcnt(6)
	s_barrier
	v_mfma_f32_16x16x32_bf16 v[44:47], v[198:201], v[68:71], v[48:51]
	v_mfma_f32_16x16x32_bf16 v[28:31], v[206:209], v[68:71], v[28:31]
	v_mfma_f32_16x16x32_bf16 v[24:27], v[198:201], v[76:79], v[24:27]
	v_mfma_f32_16x16x32_bf16 v[12:15], v[206:209], v[76:79], v[12:15]
	v_mfma_f32_16x16x32_bf16 v[20:23], v[198:201], v[178:181], v[20:23]
	v_mfma_f32_16x16x32_bf16 v[4:7], v[206:209], v[178:181], v[4:7]
	v_mfma_f32_16x16x32_bf16 v[32:35], v[198:201], v[186:189], v[32:35]
	v_mfma_f32_16x16x32_bf16 v[0:3], v[206:209], v[186:189], v[0:3]
	v_mfma_f32_16x16x32_bf16 v[84:87], v[202:205], v[72:75], v[44:47]
	v_mfma_f32_16x16x32_bf16 v[28:31], v[210:213], v[72:75], v[28:31]
	v_mfma_f32_16x16x32_bf16 v[24:27], v[202:205], v[80:83], v[24:27]
	v_mfma_f32_16x16x32_bf16 v[12:15], v[210:213], v[80:83], v[12:15]
	v_mfma_f32_16x16x32_bf16 v[20:23], v[202:205], v[182:185], v[20:23]
	v_mfma_f32_16x16x32_bf16 v[4:7], v[210:213], v[182:185], v[4:7]
	v_mfma_f32_16x16x32_bf16 v[32:35], v[202:205], v[190:193], v[32:35]
	v_mfma_f32_16x16x32_bf16 v[0:3], v[210:213], v[190:193], v[0:3]
	s_add_i32 s59, s59, 2
	s_add_u32 vcc_lo, vcc_lo, 0x100
	s_addc_u32 vcc_hi, vcc_hi, 0
	s_add_u32 s55, s55, 0x100
	s_addc_u32 s57, s57, 0
	s_cmp_gt_u32 s59, 13
	s_barrier

.LBB0_744:
	s_waitcnt vmcnt(0)
	s_cmpk_gt_u32 s5, 0xff
	s_cbranch_scc1 .LBB0_746
.LBB0_746:
	s_barrier

.LBB0_868:
	s_cmp_lt_i32 s82, 14
	s_cselect_b64 s[0:1], -1, 0
	s_and_b64 s[0:1], s[0:1], s[2:3]
	s_andn2_b64 vcc, exec, s[0:1]
	s_cbranch_vccnz .LBB0_893
	s_mov_b64 s[0:1], 0
	v_readlane_b32 s2, v254, 0
	v_mov_b32_e32 v0, v230
	s_cmpk_gt_i32 s2, 0x3ff
	v_readfirstlane_b32 s16, v230
	s_cbranch_scc1 .LBB0_893
	s_mov_b32 s41, s2
	s_ashr_i32 s17, s41, 31
	s_lshr_b32 s2, s17, 29
	s_add_i32 s4, s41, s2
	s_and_b32 s2, s4, -8
	s_sub_i32 s6, s41, s2
	s_cmp_gt_i32 s6, -1
	s_cbranch_scc0 .LBB0_872
	s_lshl_b32 s7, s6, 7
	s_ashr_i32 s2, s4, 3
	s_cbranch_execz .LBB0_873
	s_branch .LBB0_874
	s_nop 0
	s_nop 0
	s_nop 0
	s_nop 0
	s_nop 0
	s_nop 0
.LBB0_872:
	s_ashr_i32 s2, s4, 3

.LBB0_876:
	s_mov_b64 s[8:9], 0x80
	s_and_b32 s12, s4, 3
	s_add_i32 m0, s23, 0x18000
	v_lshl_add_u64 v[6:7], v[6:7], 0, s[8:9]
	s_lshl_b32 s4, s5, 13
	s_lshl_b32 s13, s12, 12
	s_waitcnt vmcnt(4)
	s_barrier
	global_load_lds_dwordx4 v[6:7], off
	v_lshl_add_u64 v[4:5], v[4:5], 0, s[8:9]
	s_add_i32 m0, s23, 0x1a000
	s_add_i32 s28, s23, 0x8000
	s_add_i32 s29, s23, 0xa000
	global_load_lds_dwordx4 v[4:5], off
	v_lshl_add_u64 v[2:3], v[2:3], 0, s[8:9]
	s_mov_b32 m0, s28
	s_add_u32 s6, s10, 0xb0080
	global_load_lds_dwordx4 v[2:3], off
	v_lshl_add_u64 v[0:1], v[0:1], 0, s[8:9]
	s_mov_b32 m0, s29
	s_addc_u32 s7, s11, 0
	global_load_lds_dwordx4 v[0:1], off
	s_add_i32 m0, s23, 0x1c000
	v_lshl_add_u64 v[0:1], s[6:7], 0, v[128:129]
	global_load_lds_dwordx4 v[0:1], off
	v_lshl_add_u64 v[0:1], s[6:7], 0, v[130:131]
	s_add_i32 m0, s23, 0x1e000
	s_sext_i32_i8 s36, s0
	global_load_lds_dwordx4 v[0:1], off
	v_lshrrev_b32_e32 v1, 1, v230
	v_and_b32_e32 v1, 24, v1
	v_and_b32_e32 v0, 15, v230
	v_lshlrev_b32_e32 v2, 1, v1
	v_lshl_or_b32 v146, s5, 6, v0
	v_lshl_or_b32 v0, v0, 6, v2
	v_lshlrev_b32_e32 v2, 2, v230
	v_and_b32_e32 v2, 32, v2
	v_bitop3_b32 v3, v0, s4, v2 bitop3:0xde
	v_bitop3_b32 v147, v0, s13, v2 bitop3:0xde
	v_lshl_or_b32 v148, s12, 6, v1
	v_lshrrev_b32_e32 v1, 1, v8
	v_mul_lo_u32 v0, v10, s1
	s_mov_b32 s0, 0xb000
	v_mad_u64_u32 v[0:1], s[6:7], v1, s0, v[0:1]
	v_or_b32_e32 v0, v0, v9
	s_mov_b64 s[4:5], 0xb0080
	v_add_lshl_u32 v0, v0, v11, 1
	v_mov_b32_e32 v1, v129
	v_lshl_add_u64 v[132:133], v[0:1], 0, s[4:5]
	v_lshrrev_b32_e32 v1, 1, v12
	v_mul_lo_u32 v0, v13, s1
	v_mad_u64_u32 v[0:1], s[0:1], v1, s0, v[0:1]
	s_waitcnt vmcnt(6)
	v_or_b32_e32 v0, v0, v14
	v_add_lshl_u32 v0, v0, v15, 1
	v_mov_b32_e32 v1, v129
	s_add_i32 s30, 0, 0x10000
	s_add_i32 s31, 0, 0x14000
	v_lshl_add_u64 v[134:135], v[0:1], 0, s[4:5]
	v_mov_b64_e32 v[136:137], 0x400
	v_mov_b64_e32 v[138:139], 0x3ff
	v_add_u32_e32 v149, s30, v147
	v_add_u32_e32 v150, 0, v3
	v_add_u32_e32 v151, s31, v147
	s_barrier
	s_cmpk_gt_u32 s16, 0xff
	s_cbranch_scc1 .Lepix_ffnout
	s_barrier
.Lepix_ffnout:
.LBB0_877:
	s_add_i32 s27, s27, 1
	s_mul_i32 s0, s27, s93
	s_mul_hi_u32 s1, s27, s92
	s_add_i32 s1, s1, s0
	s_mul_i32 s0, s27, s92
	s_add_u32 s4, s0, s41
	s_addc_u32 s5, s1, s17
	v_cmp_gt_i64_e64 s[0:1], s[4:5], v[138:139]
	v_cmp_lt_i64_e64 s[6:7], s[4:5], v[136:137]
	s_and_b64 vcc, exec, s[0:1]
	s_cbranch_vccnz .LBB0_883
	s_ashr_i32 s12, s4, 31
	s_lshr_b32 s12, s12, 29
	s_add_i32 s14, s4, s12
	s_and_b32 s12, s14, -8
	s_sub_i32 s15, s4, s12
	s_cmp_gt_i32 s15, -1
	s_mov_b64 s[12:13], -1
	s_cbranch_scc0 .LBB0_880
	s_lshl_b32 s33, s15, 7
	s_mov_b64 s[12:13], 0

.LBB0_887:
	s_add_u32 s37, s10, 0x100
	s_addc_u32 s38, s11, 0
	s_mov_b32 s39, -2
	ds_read_b128 v[140:143], v149
	ds_read_b128 v[152:155], v149 offset:1024
	ds_read_b128 v[156:159], v149 offset:2048
	ds_read_b128 v[160:163], v149 offset:3072
	s_add_u32 s10, s2, 0x100
	s_addc_u32 s11, s3, 0
	s_cmp_eq_u32 s39, 40
	s_cselect_b32 s15, s7, s11
	s_cselect_b32 s14, s6, s10
	s_cselect_b32 s13, s5, s38
	s_cselect_b32 s12, s4, s37
	v_lshl_add_u64 v[144:145], s[2:3], 0, v[132:133]
	s_add_i32 m0, s23, 0xc000
	ds_read_b128 v[164:167], v150
	ds_read_b128 v[168:171], v150 offset:1024
	ds_read_b128 v[172:175], v150 offset:2048
	ds_read_b128 v[176:179], v150 offset:3072
	ds_read_b128 v[180:183], v150 offset:4096
	ds_read_b128 v[184:187], v150 offset:5120
	ds_read_b128 v[188:191], v150 offset:6144
	ds_read_b128 v[192:195], v150 offset:7168
	global_load_lds_dwordx4 v[144:145], off
	v_lshl_add_u64 v[144:145], s[2:3], 0, v[134:135]
	s_add_i32 m0, s23, 0xe000
	s_nop 0
	global_load_lds_dwordx4 v[144:145], off
	s_cmpk_gt_u32 s16, 0xff
	s_cbranch_scc0 .Lhbar_ffnout
	s_barrier
.Lhbar_ffnout:
	s_waitcnt lgkmcnt(8)
	s_barrier
	s_waitcnt lgkmcnt(0)
	s_waitcnt lgkmcnt(0)
	v_mfma_f32_16x16x32_bf16 v[124:127], v[140:143], v[164:167], 0
	v_mfma_f32_16x16x32_bf16 v[120:123], v[156:159], v[164:167], 0
	v_mfma_f32_16x16x32_bf16 v[116:119], v[140:143], v[172:175], 0
	v_mfma_f32_16x16x32_bf16 v[112:115], v[156:159], v[172:175], 0
	v_mfma_f32_16x16x32_bf16 v[92:95], v[140:143], v[180:183], 0
	v_mfma_f32_16x16x32_bf16 v[88:91], v[156:159], v[180:183], 0
	v_mfma_f32_16x16x32_bf16 v[84:87], v[140:143], v[188:191], 0
	v_mfma_f32_16x16x32_bf16 v[80:83], v[156:159], v[188:191], 0
	v_mfma_f32_16x16x32_bf16 v[124:127], v[152:155], v[168:171], v[124:127]
	v_mfma_f32_16x16x32_bf16 v[120:123], v[160:163], v[168:171], v[120:123]
	v_mfma_f32_16x16x32_bf16 v[116:119], v[152:155], v[176:179], v[116:119]
	v_mfma_f32_16x16x32_bf16 v[112:115], v[160:163], v[176:179], v[112:115]
	v_mfma_f32_16x16x32_bf16 v[92:95], v[152:155], v[184:187], v[92:95]
	v_mfma_f32_16x16x32_bf16 v[88:91], v[160:163], v[184:187], v[88:91]
	v_mfma_f32_16x16x32_bf16 v[84:87], v[152:155], v[192:195], v[84:87]
	v_mfma_f32_16x16x32_bf16 v[80:83], v[160:163], v[192:195], v[80:83]
	s_barrier
	s_add_i32 s2, s30, s22
	v_lshl_add_u64 v[144:145], s[12:13], 0, v[128:129]
	s_mov_b32 m0, s2
	ds_read_b128 v[196:199], v151
	ds_read_b128 v[200:203], v151 offset:1024
	ds_read_b128 v[204:207], v151 offset:2048
	ds_read_b128 v[208:211], v151 offset:3072
	global_load_lds_dwordx4 v[144:145], off
	v_lshl_add_u64 v[212:213], s[12:13], 0, v[130:131]
	s_add_i32 m0, s2, 0x2000
	s_nop 0
	global_load_lds_dwordx4 v[212:213], off
	s_barrier
	s_waitcnt lgkmcnt(0)
	s_waitcnt lgkmcnt(0)
	v_mfma_f32_16x16x32_bf16 v[108:111], v[196:199], v[164:167], 0
	v_mfma_f32_16x16x32_bf16 v[104:107], v[204:207], v[164:167], 0
	v_mfma_f32_16x16x32_bf16 v[100:103], v[196:199], v[172:175], 0
	v_mfma_f32_16x16x32_bf16 v[96:99], v[204:207], v[172:175], 0
	v_mfma_f32_16x16x32_bf16 v[76:79], v[196:199], v[180:183], 0
	v_mfma_f32_16x16x32_bf16 v[72:75], v[204:207], v[180:183], 0
	v_mfma_f32_16x16x32_bf16 v[68:71], v[196:199], v[188:191], 0
	v_mfma_f32_16x16x32_bf16 v[64:67], v[204:207], v[188:191], 0
	v_mfma_f32_16x16x32_bf16 v[108:111], v[200:203], v[168:171], v[108:111]
	v_mfma_f32_16x16x32_bf16 v[104:107], v[208:211], v[168:171], v[104:107]
	v_mfma_f32_16x16x32_bf16 v[100:103], v[200:203], v[176:179], v[100:103]
	v_mfma_f32_16x16x32_bf16 v[96:99], v[208:211], v[176:179], v[96:99]
	v_mfma_f32_16x16x32_bf16 v[76:79], v[200:203], v[184:187], v[76:79]
	v_mfma_f32_16x16x32_bf16 v[72:75], v[208:211], v[184:187], v[72:75]
	v_mfma_f32_16x16x32_bf16 v[68:71], v[200:203], v[192:195], v[68:71]
	v_mfma_f32_16x16x32_bf16 v[64:67], v[208:211], v[192:195], v[64:67]
	s_mov_b32 m0, s23
	v_lshl_add_u64 v[214:215], s[14:15], 0, v[128:129]
	s_barrier
	ds_read_b128 v[164:167], v150 offset:16384
	ds_read_b128 v[168:171], v150 offset:17408
	ds_read_b128 v[172:175], v150 offset:18432
	ds_read_b128 v[176:179], v150 offset:19456
	ds_read_b128 v[180:183], v150 offset:20480
	ds_read_b128 v[184:187], v150 offset:21504
	ds_read_b128 v[188:191], v150 offset:22528
	ds_read_b128 v[192:195], v150 offset:23552
	global_load_lds_dwordx4 v[214:215], off
	v_lshl_add_u64 v[216:217], s[14:15], 0, v[130:131]
	s_mov_b32 m0, s24
	s_nop 0
	global_load_lds_dwordx4 v[216:217], off
	s_barrier
	s_waitcnt lgkmcnt(0)
	s_waitcnt lgkmcnt(0)
	v_mfma_f32_16x16x32_bf16 v[60:63], v[140:143], v[164:167], 0
	v_mfma_f32_16x16x32_bf16 v[56:59], v[156:159], v[164:167], 0
	v_mfma_f32_16x16x32_bf16 v[52:55], v[140:143], v[172:175], 0
	v_mfma_f32_16x16x32_bf16 v[48:51], v[156:159], v[172:175], 0
	v_mfma_f32_16x16x32_bf16 v[28:31], v[140:143], v[180:183], 0
	v_mfma_f32_16x16x32_bf16 v[24:27], v[156:159], v[180:183], 0
	v_mfma_f32_16x16x32_bf16 v[16:19], v[140:143], v[188:191], 0
	v_mfma_f32_16x16x32_bf16 v[8:11], v[156:159], v[188:191], 0
	v_mfma_f32_16x16x32_bf16 v[60:63], v[152:155], v[168:171], v[60:63]
	v_mfma_f32_16x16x32_bf16 v[56:59], v[160:163], v[168:171], v[56:59]
	v_mfma_f32_16x16x32_bf16 v[52:55], v[152:155], v[176:179], v[52:55]
	v_mfma_f32_16x16x32_bf16 v[48:51], v[160:163], v[176:179], v[48:51]
	v_mfma_f32_16x16x32_bf16 v[28:31], v[152:155], v[184:187], v[28:31]
	v_mfma_f32_16x16x32_bf16 v[24:27], v[160:163], v[184:187], v[24:27]
	v_mfma_f32_16x16x32_bf16 v[16:19], v[152:155], v[192:195], v[16:19]
	v_mfma_f32_16x16x32_bf16 v[8:11], v[160:163], v[192:195], v[8:11]
	s_barrier
	s_add_u32 s2, s12, 0xb0000
	s_addc_u32 s3, s13, 0
	s_add_i32 s40, s31, s22
	v_lshl_add_u64 v[140:141], s[2:3], 0, v[128:129]
	s_mov_b32 m0, s40
	s_nop 0
	global_load_lds_dwordx4 v[140:141], off
	v_lshl_add_u64 v[140:141], s[2:3], 0, v[130:131]
	s_add_i32 m0, s40, 0x2000
	s_nop 0
	global_load_lds_dwordx4 v[140:141], off
	s_waitcnt vmcnt(6)
	s_barrier
	v_mfma_f32_16x16x32_bf16 v[44:47], v[196:199], v[164:167], 0
	v_mfma_f32_16x16x32_bf16 v[40:43], v[204:207], v[164:167], 0
	v_mfma_f32_16x16x32_bf16 v[36:39], v[196:199], v[172:175], 0
	v_mfma_f32_16x16x32_bf16 v[32:35], v[204:207], v[172:175], 0
	v_mfma_f32_16x16x32_bf16 v[20:23], v[196:199], v[180:183], 0
	v_mfma_f32_16x16x32_bf16 v[12:15], v[204:207], v[180:183], 0
	v_mfma_f32_16x16x32_bf16 v[4:7], v[196:199], v[188:191], 0
	v_mfma_f32_16x16x32_bf16 v[0:3], v[204:207], v[188:191], 0
	v_mfma_f32_16x16x32_bf16 v[44:47], v[200:203], v[168:171], v[44:47]
	v_mfma_f32_16x16x32_bf16 v[40:43], v[208:211], v[168:171], v[40:43]
	v_mfma_f32_16x16x32_bf16 v[36:39], v[200:203], v[176:179], v[36:39]
	v_mfma_f32_16x16x32_bf16 v[32:35], v[208:211], v[176:179], v[32:35]
	v_mfma_f32_16x16x32_bf16 v[20:23], v[200:203], v[184:187], v[20:23]
	v_mfma_f32_16x16x32_bf16 v[12:15], v[208:211], v[184:187], v[12:15]
	v_mfma_f32_16x16x32_bf16 v[4:7], v[200:203], v[192:195], v[4:7]
	v_mfma_f32_16x16x32_bf16 v[0:3], v[208:211], v[192:195], v[0:3]
	s_add_i32 s40, 0, 0x18000
	v_add_u32_e32 v160, s40, v147
	s_barrier
	ds_read_b128 v[140:143], v160
	ds_read_b128 v[152:155], v160 offset:1024
	ds_read_b128 v[156:159], v160 offset:2048
	ds_read_b128 v[160:163], v160 offset:3072
	s_add_u32 s2, s14, 0xb0000
	s_addc_u32 s3, s15, 0
	s_mov_b32 m0, s25
	v_lshl_add_u64 v[196:197], s[2:3], 0, v[128:129]
	ds_read_b128 v[164:167], v150 offset:32768
	ds_read_b128 v[168:171], v150 offset:33792
	ds_read_b128 v[172:175], v150 offset:34816
	ds_read_b128 v[176:179], v150 offset:35840
	ds_read_b128 v[180:183], v150 offset:36864
	ds_read_b128 v[184:187], v150 offset:37888
	ds_read_b128 v[188:191], v150 offset:38912
	ds_read_b128 v[192:195], v150 offset:39936
	global_load_lds_dwordx4 v[196:197], off
	v_lshl_add_u64 v[196:197], s[2:3], 0, v[130:131]
	s_mov_b32 m0, s26
	s_nop 0
	global_load_lds_dwordx4 v[196:197], off
	s_waitcnt lgkmcnt(8)
	s_barrier
	s_waitcnt lgkmcnt(0)
	s_waitcnt lgkmcnt(0)
	v_mfma_f32_16x16x32_bf16 v[124:127], v[140:143], v[164:167], v[124:127]
	v_mfma_f32_16x16x32_bf16 v[120:123], v[156:159], v[164:167], v[120:123]
	v_mfma_f32_16x16x32_bf16 v[116:119], v[140:143], v[172:175], v[116:119]
	v_mfma_f32_16x16x32_bf16 v[112:115], v[156:159], v[172:175], v[112:115]
	v_mfma_f32_16x16x32_bf16 v[92:95], v[140:143], v[180:183], v[92:95]
	v_mfma_f32_16x16x32_bf16 v[88:91], v[156:159], v[180:183], v[88:91]
	v_mfma_f32_16x16x32_bf16 v[84:87], v[140:143], v[188:191], v[84:87]
	v_mfma_f32_16x16x32_bf16 v[80:83], v[156:159], v[188:191], v[80:83]
	v_mfma_f32_16x16x32_bf16 v[124:127], v[152:155], v[168:171], v[124:127]
	v_mfma_f32_16x16x32_bf16 v[120:123], v[160:163], v[168:171], v[120:123]
	v_mfma_f32_16x16x32_bf16 v[116:119], v[152:155], v[176:179], v[116:119]
	v_mfma_f32_16x16x32_bf16 v[112:115], v[160:163], v[176:179], v[112:115]
	v_mfma_f32_16x16x32_bf16 v[92:95], v[152:155], v[184:187], v[92:95]
	v_mfma_f32_16x16x32_bf16 v[88:91], v[160:163], v[184:187], v[88:91]
	v_mfma_f32_16x16x32_bf16 v[84:87], v[152:155], v[192:195], v[84:87]
	v_mfma_f32_16x16x32_bf16 v[80:83], v[160:163], v[192:195], v[80:83]
	s_barrier
	s_add_i32 s14, 0, 0x1c000
	s_add_i32 s2, s40, s22
	v_add_u32_e32 v208, s14, v147
	v_lshl_add_u64 v[144:145], v[144:145], 0, s[8:9]
	s_mov_b32 m0, s2
	ds_read_b128 v[196:199], v208
	ds_read_b128 v[200:203], v208 offset:1024
	ds_read_b128 v[204:207], v208 offset:2048
	ds_read_b128 v[208:211], v208 offset:3072
	global_load_lds_dwordx4 v[144:145], off
	v_lshl_add_u64 v[144:145], v[212:213], 0, s[8:9]
	s_add_i32 m0, s2, 0x2000
	s_nop 0
	global_load_lds_dwordx4 v[144:145], off
	s_barrier
	s_waitcnt lgkmcnt(0)
	s_waitcnt lgkmcnt(0)
	v_mfma_f32_16x16x32_bf16 v[108:111], v[196:199], v[164:167], v[108:111]
	v_mfma_f32_16x16x32_bf16 v[104:107], v[204:207], v[164:167], v[104:107]
	v_mfma_f32_16x16x32_bf16 v[100:103], v[196:199], v[172:175], v[100:103]
	v_mfma_f32_16x16x32_bf16 v[96:99], v[204:207], v[172:175], v[96:99]
	v_mfma_f32_16x16x32_bf16 v[76:79], v[196:199], v[180:183], v[76:79]
	v_mfma_f32_16x16x32_bf16 v[72:75], v[204:207], v[180:183], v[72:75]
	v_mfma_f32_16x16x32_bf16 v[68:71], v[196:199], v[188:191], v[68:71]
	v_mfma_f32_16x16x32_bf16 v[64:67], v[204:207], v[188:191], v[64:67]
	v_mfma_f32_16x16x32_bf16 v[108:111], v[200:203], v[168:171], v[108:111]
	v_mfma_f32_16x16x32_bf16 v[104:107], v[208:211], v[168:171], v[104:107]
	v_mfma_f32_16x16x32_bf16 v[100:103], v[200:203], v[176:179], v[100:103]
	v_mfma_f32_16x16x32_bf16 v[96:99], v[208:211], v[176:179], v[96:99]
	v_mfma_f32_16x16x32_bf16 v[76:79], v[200:203], v[184:187], v[76:79]
	v_mfma_f32_16x16x32_bf16 v[72:75], v[208:211], v[184:187], v[72:75]
	v_mfma_f32_16x16x32_bf16 v[68:71], v[200:203], v[192:195], v[68:71]
	v_mfma_f32_16x16x32_bf16 v[64:67], v[208:211], v[192:195], v[64:67]
	s_mov_b32 m0, s28
	v_lshl_add_u64 v[144:145], v[214:215], 0, s[8:9]
	s_barrier
	ds_read_b128 v[164:167], v150 offset:49152
	ds_read_b128 v[168:171], v150 offset:50176
	ds_read_b128 v[172:175], v150 offset:51200
	ds_read_b128 v[176:179], v150 offset:52224
	ds_read_b128 v[180:183], v150 offset:53248
	ds_read_b128 v[184:187], v150 offset:54272
	ds_read_b128 v[188:191], v150 offset:55296
	ds_read_b128 v[192:195], v150 offset:56320
	global_load_lds_dwordx4 v[144:145], off
	v_lshl_add_u64 v[144:145], v[216:217], 0, s[8:9]
	s_mov_b32 m0, s29
	s_nop 0
	global_load_lds_dwordx4 v[144:145], off
	s_barrier
	s_waitcnt lgkmcnt(0)
	s_waitcnt lgkmcnt(0)
	v_mfma_f32_16x16x32_bf16 v[60:63], v[140:143], v[164:167], v[60:63]
	v_mfma_f32_16x16x32_bf16 v[56:59], v[156:159], v[164:167], v[56:59]
	v_mfma_f32_16x16x32_bf16 v[52:55], v[140:143], v[172:175], v[52:55]
	v_mfma_f32_16x16x32_bf16 v[48:51], v[156:159], v[172:175], v[48:51]
	v_mfma_f32_16x16x32_bf16 v[28:31], v[140:143], v[180:183], v[28:31]
	v_mfma_f32_16x16x32_bf16 v[24:27], v[156:159], v[180:183], v[24:27]
	v_mfma_f32_16x16x32_bf16 v[16:19], v[140:143], v[188:191], v[16:19]
	v_mfma_f32_16x16x32_bf16 v[8:11], v[156:159], v[188:191], v[8:11]
	v_mfma_f32_16x16x32_bf16 v[60:63], v[152:155], v[168:171], v[60:63]
	v_mfma_f32_16x16x32_bf16 v[56:59], v[160:163], v[168:171], v[56:59]
	v_mfma_f32_16x16x32_bf16 v[52:55], v[152:155], v[176:179], v[52:55]
	v_mfma_f32_16x16x32_bf16 v[48:51], v[160:163], v[176:179], v[48:51]
	v_mfma_f32_16x16x32_bf16 v[28:31], v[152:155], v[184:187], v[28:31]
	v_mfma_f32_16x16x32_bf16 v[24:27], v[160:163], v[184:187], v[24:27]
	v_mfma_f32_16x16x32_bf16 v[16:19], v[152:155], v[192:195], v[16:19]
	v_mfma_f32_16x16x32_bf16 v[8:11], v[160:163], v[192:195], v[8:11]
	s_barrier
	s_add_u32 s2, s12, 0xb0080
	s_addc_u32 s3, s13, 0
	s_add_i32 s12, s14, s22
	v_lshl_add_u64 v[140:141], s[2:3], 0, v[128:129]
	s_mov_b32 m0, s12
	s_nop 0
	global_load_lds_dwordx4 v[140:141], off
	v_lshl_add_u64 v[140:141], s[2:3], 0, v[130:131]
	s_add_i32 m0, s12, 0x2000
	s_nop 0
	global_load_lds_dwordx4 v[140:141], off
	s_waitcnt vmcnt(6)
	s_barrier
	v_mfma_f32_16x16x32_bf16 v[44:47], v[196:199], v[164:167], v[44:47]
	v_mfma_f32_16x16x32_bf16 v[40:43], v[204:207], v[164:167], v[40:43]
	v_mfma_f32_16x16x32_bf16 v[36:39], v[196:199], v[172:175], v[36:39]
	v_mfma_f32_16x16x32_bf16 v[32:35], v[204:207], v[172:175], v[32:35]
	v_mfma_f32_16x16x32_bf16 v[20:23], v[196:199], v[180:183], v[20:23]
	v_mfma_f32_16x16x32_bf16 v[12:15], v[204:207], v[180:183], v[12:15]
	v_mfma_f32_16x16x32_bf16 v[4:7], v[196:199], v[188:191], v[4:7]
	v_mfma_f32_16x16x32_bf16 v[0:3], v[204:207], v[188:191], v[0:3]
	v_mfma_f32_16x16x32_bf16 v[44:47], v[200:203], v[168:171], v[44:47]
	v_mfma_f32_16x16x32_bf16 v[40:43], v[208:211], v[168:171], v[40:43]
	v_mfma_f32_16x16x32_bf16 v[36:39], v[200:203], v[176:179], v[36:39]
	v_mfma_f32_16x16x32_bf16 v[32:35], v[208:211], v[176:179], v[32:35]
	v_mfma_f32_16x16x32_bf16 v[20:23], v[200:203], v[184:187], v[20:23]
	v_mfma_f32_16x16x32_bf16 v[12:15], v[208:211], v[184:187], v[12:15]
	v_mfma_f32_16x16x32_bf16 v[4:7], v[200:203], v[192:195], v[4:7]
	v_mfma_f32_16x16x32_bf16 v[0:3], v[208:211], v[192:195], v[0:3]
	s_add_i32 s39, s39, 2
	s_add_u32 s37, s37, 0x100
	s_addc_u32 s38, s38, 0
	s_cmp_gt_u32 s39, 41
	s_mov_b64 s[2:3], s[10:11]
	s_barrier

.Lepi0_ffnout:
	v_lshl_or_b32 v140, s36, 8, v148
	v_lshl_add_u32 v144, s35, 8, v146
	v_ashrrev_i32_e32 v141, 31, v140
	v_lshlrev_b64 v[140:141], 2, v[140:141]
	v_ashrrev_i32_e32 v145, 31, v144
	v_lshl_add_u64 v[142:143], s[78:79], 0, v[140:141]
	v_lshlrev_b64 v[184:185], 12, v[144:145]
	v_lshl_add_u64 v[164:165], v[142:143], 0, v[184:185]
	v_or_b32_e32 v168, 16, v144
	global_load_dwordx4 v[152:155], v[164:165], off offset:16
	global_load_dwordx4 v[156:159], v[164:165], off
	global_load_dwordx4 v[160:163], v[164:165], off offset:144
	s_nop 0
	global_load_dwordx4 v[164:167], v[164:165], off offset:128
	v_ashrrev_i32_e32 v169, 31, v168
	v_lshlrev_b64 v[186:187], 12, v[168:169]
	v_lshl_add_u64 v[180:181], v[142:143], 0, v[186:187]
	global_load_dwordx4 v[168:171], v[180:181], off offset:16
	global_load_dwordx4 v[172:175], v[180:181], off
	global_load_dwordx4 v[176:179], v[180:181], off offset:144
	s_nop 0
	global_load_dwordx4 v[180:183], v[180:181], off offset:128
	s_and_b64 vcc, exec, s[0:1]
	s_mov_b32 s36, s34
	s_mov_b32 s35, s33
	s_mov_b64 s[10:11], s[4:5]
	s_mov_b64 s[2:3], s[6:7]
	s_waitcnt vmcnt(0)
	v_pk_add_f32 v[120:121], v[120:121], v[152:153]
	v_lshl_add_u64 v[152:153], s[78:79], 0, v[184:185]
	v_pk_add_f32 v[126:127], v[126:127], v[158:159]
	v_pk_add_f32 v[124:125], v[124:125], v[156:157]
	v_pk_add_f32 v[108:109], v[108:109], v[164:165]
	v_lshl_add_u64 v[152:153], v[152:153], 0, v[140:141]
	v_pk_add_f32 v[122:123], v[122:123], v[154:155]
	v_pk_add_f32 v[110:111], v[110:111], v[166:167]
	v_pk_add_f32 v[106:107], v[106:107], v[162:163]
	v_pk_add_f32 v[104:105], v[104:105], v[160:161]
	global_store_dwordx4 v[152:153], v[124:127], off nt
	global_store_dwordx4 v[152:153], v[120:123], off offset:16 nt
	global_store_dwordx4 v[152:153], v[108:111], off offset:128 nt
	global_store_dwordx4 v[152:153], v[104:107], off offset:144 nt
	v_pk_add_f32 v[96:97], v[96:97], v[176:177]
	v_pk_add_f32 v[108:109], v[112:113], v[168:169]
	v_lshl_add_u64 v[112:113], s[78:79], 0, v[186:187]
	v_pk_add_f32 v[106:107], v[118:119], v[174:175]
	v_pk_add_f32 v[104:105], v[116:117], v[172:173]
	v_lshl_add_u64 v[112:113], v[112:113], 0, v[140:141]
	v_pk_add_f32 v[110:111], v[114:115], v[170:171]
	v_pk_add_f32 v[102:103], v[102:103], v[182:183]
	v_pk_add_f32 v[100:101], v[100:101], v[180:181]
	v_pk_add_f32 v[98:99], v[98:99], v[178:179]
	global_store_dwordx4 v[112:113], v[104:107], off nt
	global_store_dwordx4 v[112:113], v[108:111], off offset:16 nt
	global_store_dwordx4 v[112:113], v[100:103], off offset:128 nt
	global_store_dwordx4 v[112:113], v[96:99], off offset:144 nt
	v_or_b32_e32 v112, 48, v144
	v_ashrrev_i32_e32 v113, 31, v112
	v_or_b32_e32 v96, 32, v144
	v_ashrrev_i32_e32 v97, 31, v96
	v_lshlrev_b64 v[152:153], 12, v[96:97]
	v_lshl_add_u64 v[108:109], v[142:143], 0, v[152:153]
	global_load_dwordx4 v[96:99], v[108:109], off offset:16
	global_load_dwordx4 v[100:103], v[108:109], off
	global_load_dwordx4 v[104:107], v[108:109], off offset:144
	s_nop 0
	global_load_dwordx4 v[108:111], v[108:109], off offset:128
	v_lshlrev_b64 v[154:155], 12, v[112:113]
	v_lshl_add_u64 v[124:125], v[142:143], 0, v[154:155]
	global_load_dwordx4 v[112:115], v[124:125], off offset:16
	global_load_dwordx4 v[116:119], v[124:125], off
	global_load_dwordx4 v[120:123], v[124:125], off offset:144
	s_nop 0
	global_load_dwordx4 v[124:127], v[124:125], off offset:128
	s_waitcnt vmcnt(0)
	v_pk_add_f32 v[88:89], v[88:89], v[96:97]
	v_lshl_add_u64 v[96:97], s[78:79], 0, v[152:153]
	v_pk_add_f32 v[94:95], v[94:95], v[102:103]
	v_pk_add_f32 v[92:93], v[92:93], v[100:101]
	v_pk_add_f32 v[76:77], v[76:77], v[108:109]
	v_lshl_add_u64 v[96:97], v[96:97], 0, v[140:141]
	v_pk_add_f32 v[90:91], v[90:91], v[98:99]
	v_pk_add_f32 v[78:79], v[78:79], v[110:111]
	v_pk_add_f32 v[74:75], v[74:75], v[106:107]
	v_pk_add_f32 v[72:73], v[72:73], v[104:105]
	global_store_dwordx4 v[96:97], v[92:95], off nt
	global_store_dwordx4 v[96:97], v[88:91], off offset:16 nt
	global_store_dwordx4 v[96:97], v[76:79], off offset:128 nt
	global_store_dwordx4 v[96:97], v[72:75], off offset:144 nt
	v_pk_add_f32 v[64:65], v[64:65], v[120:121]
	v_pk_add_f32 v[76:77], v[80:81], v[112:113]
	v_lshl_add_u64 v[80:81], s[78:79], 0, v[154:155]
	v_pk_add_f32 v[74:75], v[86:87], v[118:119]
	v_pk_add_f32 v[72:73], v[84:85], v[116:117]
	v_lshl_add_u64 v[80:81], v[80:81], 0, v[140:141]
	v_pk_add_f32 v[78:79], v[82:83], v[114:115]
	v_pk_add_f32 v[70:71], v[70:71], v[126:127]
	v_pk_add_f32 v[68:69], v[68:69], v[124:125]
	v_pk_add_f32 v[66:67], v[66:67], v[122:123]
	global_store_dwordx4 v[80:81], v[72:75], off nt
	global_store_dwordx4 v[80:81], v[76:79], off offset:16 nt
	global_store_dwordx4 v[80:81], v[68:71], off offset:128 nt
	global_store_dwordx4 v[80:81], v[64:67], off offset:144 nt
	s_nop 1
	v_add_u32_e32 v64, 0x80, v144
	v_ashrrev_i32_e32 v65, 31, v64
	v_lshlrev_b64 v[96:97], 12, v[64:65]
	v_lshl_add_u64 v[80:81], v[142:143], 0, v[96:97]
	global_load_dwordx4 v[64:67], v[80:81], off offset:16
	global_load_dwordx4 v[68:71], v[80:81], off
	global_load_dwordx4 v[72:75], v[80:81], off offset:144
	global_load_dwordx4 v[76:79], v[80:81], off offset:128
	v_add_u32_e32 v80, 0x90, v144
	v_ashrrev_i32_e32 v81, 31, v80
	v_lshlrev_b64 v[98:99], 12, v[80:81]
	v_lshl_add_u64 v[100:101], v[142:143], 0, v[98:99]
	global_load_dwordx4 v[80:83], v[100:101], off offset:16
	global_load_dwordx4 v[84:87], v[100:101], off
	global_load_dwordx4 v[88:91], v[100:101], off offset:144
	global_load_dwordx4 v[92:95], v[100:101], off offset:128
	s_waitcnt vmcnt(0)
	v_pk_add_f32 v[56:57], v[56:57], v[64:65]
	v_lshl_add_u64 v[64:65], s[78:79], 0, v[96:97]
	v_pk_add_f32 v[62:63], v[62:63], v[70:71]
	v_pk_add_f32 v[60:61], v[60:61], v[68:69]
	v_pk_add_f32 v[44:45], v[44:45], v[76:77]
	v_lshl_add_u64 v[64:65], v[64:65], 0, v[140:141]
	v_pk_add_f32 v[58:59], v[58:59], v[66:67]
	v_pk_add_f32 v[46:47], v[46:47], v[78:79]
	v_pk_add_f32 v[42:43], v[42:43], v[74:75]
	v_pk_add_f32 v[40:41], v[40:41], v[72:73]
	global_store_dwordx4 v[64:65], v[60:63], off nt
	global_store_dwordx4 v[64:65], v[56:59], off offset:16 nt
	global_store_dwordx4 v[64:65], v[44:47], off offset:128 nt
	global_store_dwordx4 v[64:65], v[40:43], off offset:144 nt
	v_pk_add_f32 v[32:33], v[32:33], v[88:89]
	v_pk_add_f32 v[44:45], v[48:49], v[80:81]
	v_lshl_add_u64 v[48:49], s[78:79], 0, v[98:99]
	v_pk_add_f32 v[42:43], v[54:55], v[86:87]
	v_pk_add_f32 v[40:41], v[52:53], v[84:85]
	v_lshl_add_u64 v[48:49], v[48:49], 0, v[140:141]
	v_pk_add_f32 v[46:47], v[50:51], v[82:83]
	v_pk_add_f32 v[38:39], v[38:39], v[94:95]
	v_pk_add_f32 v[36:37], v[36:37], v[92:93]
	v_pk_add_f32 v[34:35], v[34:35], v[90:91]
	global_store_dwordx4 v[48:49], v[40:43], off nt
	global_store_dwordx4 v[48:49], v[44:47], off offset:16 nt
	global_store_dwordx4 v[48:49], v[36:39], off offset:128 nt
	global_store_dwordx4 v[48:49], v[32:35], off offset:144 nt
	s_nop 1
	v_add_u32_e32 v32, 0xa0, v144
	v_ashrrev_i32_e32 v33, 31, v32
	v_lshlrev_b64 v[60:61], 12, v[32:33]
	v_lshl_add_u64 v[48:49], v[142:143], 0, v[60:61]
	global_load_dwordx4 v[40:43], v[48:49], off offset:16
	global_load_dwordx4 v[44:47], v[48:49], off
	global_load_dwordx4 v[32:35], v[48:49], off offset:144
	global_load_dwordx4 v[36:39], v[48:49], off offset:128
	v_add_u32_e32 v48, 0xb0, v144
	v_ashrrev_i32_e32 v49, 31, v48
	v_lshlrev_b64 v[62:63], 12, v[48:49]
	v_lshl_add_u64 v[68:69], v[142:143], 0, v[62:63]
	global_load_dwordx4 v[48:51], v[68:69], off offset:16
	global_load_dwordx4 v[56:59], v[68:69], off
	global_load_dwordx4 v[52:55], v[68:69], off offset:144
	global_load_dwordx4 v[64:67], v[68:69], off offset:128
	s_waitcnt vmcnt(0)
	v_pk_add_f32 v[26:27], v[26:27], v[42:43]
	v_pk_add_f32 v[30:31], v[30:31], v[46:47]
	v_pk_add_f32 v[12:13], v[12:13], v[32:33]
	v_lshl_add_u64 v[32:33], s[78:79], 0, v[60:61]
	v_pk_add_f32 v[28:29], v[28:29], v[44:45]
	v_lshl_add_u64 v[32:33], v[32:33], 0, v[140:141]
	v_pk_add_f32 v[24:25], v[24:25], v[40:41]
	v_pk_add_f32 v[22:23], v[22:23], v[38:39]
	v_pk_add_f32 v[20:21], v[20:21], v[36:37]
	v_pk_add_f32 v[14:15], v[14:15], v[34:35]
	global_store_dwordx4 v[32:33], v[28:31], off nt
	global_store_dwordx4 v[32:33], v[24:27], off offset:16 nt
	global_store_dwordx4 v[32:33], v[20:23], off offset:128 nt
	global_store_dwordx4 v[32:33], v[12:15], off offset:144 nt
	v_pk_add_f32 v[10:11], v[10:11], v[50:51]
	v_pk_add_f32 v[8:9], v[8:9], v[48:49]
	v_pk_add_f32 v[12:13], v[16:17], v[56:57]
	v_lshl_add_u64 v[16:17], s[78:79], 0, v[62:63]
	v_pk_add_f32 v[14:15], v[18:19], v[58:59]
	v_lshl_add_u64 v[16:17], v[16:17], 0, v[140:141]
	v_pk_add_f32 v[6:7], v[6:7], v[66:67]
	v_pk_add_f32 v[4:5], v[4:5], v[64:65]
	v_pk_add_f32 v[2:3], v[2:3], v[54:55]
	v_pk_add_f32 v[0:1], v[0:1], v[52:53]
	global_store_dwordx4 v[16:17], v[12:15], off nt
	global_store_dwordx4 v[16:17], v[8:11], off offset:16 nt
	global_store_dwordx4 v[16:17], v[4:7], off offset:128 nt
	global_store_dwordx4 v[16:17], v[0:3], off offset:144 nt
	s_cbranch_vccz .LBB0_877
	s_waitcnt vmcnt(0)
	s_cmpk_gt_u32 s16, 0xff
	s_cbranch_scc1 .LBB0_892
